# removed the 64 per-phase s_setprio 1/0 flips around the MFMA blocks of the four GEMM K-loops
# speedup vs baseline: 1.0711x; 1.0029x over previous
; #define PG8_STAGE(bufoff, gbase, voff) do { _Pragma("unroll") for (int _i = 0; _i < 2; ++_i) \
;         __builtin_amdgcn_global_load_lds((const unsigned*)((const char*)(gbase) + (voff)[_i]), (LAS unsigned*)(lds + (bufoff) + ldsw + _i * 8192), 16, 0, 0); } while (0)
; #define PG8_LDA(dst, b, h) do { _Pragma("unroll") for (int m = 0; m < 4; ++m) _Pragma("unroll") for (int k = 0; k < 2; ++k) dst[m][k] = *(const LAS bf16x8*)(lds + PG8_SA(b, h) + aoff + m * 2048 + k * 1024); } while (0)
; #define PG8_LDB(dst, b, h) do { _Pragma("unroll") for (int n = 0; n < 2; ++n) _Pragma("unroll") for (int k = 0; k < 2; ++k) dst[n][k] = *(const LAS bf16x8*)(lds + PG8_SB(b, h) + boff + n * 2048 + k * 1024); } while (0)
; #define PG8_MMA(ai, bj, At, Bt) do { __builtin_amdgcn_s_setprio(1); _Pragma("unroll") for (int m = 0; m < 4; ++m) _Pragma("unroll") for (int n = 0; n < 2; ++n) _Pragma("unroll") for (int k = 0; k < 2; ++k) \
;         acc[ai][bj][m][n] = __builtin_amdgcn_mfma_f32_16x16x32_bf16(Bt[n][k], At[m][k], acc[ai][bj][m][n], 0, 0, 0); __builtin_amdgcn_s_setprio(0); } while (0)
; #define PG8_WAIT_V(n) asm volatile("s_waitcnt vmcnt(" #n ")" ::: "memory")
; #define PG8_WAIT_L(n) asm volatile("s_waitcnt lgkmcnt(" #n ")" ::: "memory")
; #define PG8_BAR __builtin_amdgcn_s_barrier()
; #define PG8_SCHED __builtin_amdgcn_sched_barrier(0)
; template <class Epi>
; __device__ __forceinline__ void gemm_phase(LAS unsigned char* lds, const Gemm g, const StaticOrder& S, const Epi& E, float* smem = nullptr) {
;     ...
;             PG8_LDB(B0, 0, 0); PG8_SCHED; PG8_LDA(At, 0, 0); PG8_STAGE(PG8_SA(1, 1), a1 + hstep, voffA);
;             PG8_WAIT_L(8); PG8_BAR; PG8_WAIT_L(0); PG8_MMA(0, 0, At, B0); PG8_BAR; PG8_SCHED;
;             PG8_LDB(B1, 0, 1); PG8_STAGE(PG8_SB(0, 0), b2, voffA);
;             PG8_BAR; PG8_WAIT_L(0); PG8_MMA(0, 1, At, B1); PG8_BAR;
;             PG8_LDA(At, 0, 1); PG8_STAGE(PG8_SA(0, 0), a2, voffA);
;             PG8_BAR; PG8_WAIT_L(0); PG8_MMA(1, 0, At, B0); PG8_BAR; PG8_SCHED;
;             PG8_STAGE(PG8_SB(0, 1), b2 + hstep, voffA);
;             PG8_WAIT_V(6); PG8_BAR; PG8_MMA(1, 1, At, B1); PG8_BAR;
.LBB0_212:
	ds_read_b128 v[128:131], v185
	ds_read_b128 v[132:135], v185 offset:1024
	ds_read_b128 v[152:155], v185 offset:2048
	ds_read_b128 v[156:159], v185 offset:3072
	s_add_u32 s8, s6, 0xfffc0080
	s_addc_u32 s9, s7, -1
	s_cmp_eq_u32 s80, 12
	s_cselect_b32 s11, s1, s9
	s_cselect_b32 s10, s5, s8
	s_cselect_b32 s9, s61, s75
	s_cselect_b32 s8, s64, s73
	v_lshl_add_u64 v[180:181], s[6:7], 0, v[144:145]
	s_add_i32 m0, s86, 0xc000
	ds_read_b128 v[160:163], v186
	ds_read_b128 v[164:167], v186 offset:1024
	ds_read_b128 v[168:171], v186 offset:2048
	ds_read_b128 v[172:175], v186 offset:3072
	ds_read_b128 v[176:179], v186 offset:4096
	ds_read_b128 v[190:193], v186 offset:5120
	ds_read_b128 v[194:197], v186 offset:6144
	ds_read_b128 v[198:201], v186 offset:7168
	global_load_lds_dwordx4 v[180:181], off
	v_lshl_add_u64 v[180:181], s[6:7], 0, v[146:147]
	s_add_i32 m0, s86, 0xe000
	s_nop 0
	global_load_lds_dwordx4 v[180:181], off
	s_waitcnt lgkmcnt(8)
	s_barrier
	s_waitcnt lgkmcnt(0)
	s_waitcnt lgkmcnt(0)
	v_mfma_f32_16x16x32_bf16 v[124:127], v[128:131], v[160:163], v[124:127]
	v_mfma_f32_16x16x32_bf16 v[120:123], v[152:155], v[160:163], v[120:123]
	v_mfma_f32_16x16x32_bf16 v[108:111], v[128:131], v[168:171], v[108:111]
	v_mfma_f32_16x16x32_bf16 v[104:107], v[152:155], v[168:171], v[104:107]
	v_mfma_f32_16x16x32_bf16 v[92:95], v[128:131], v[176:179], v[92:95]
	v_mfma_f32_16x16x32_bf16 v[88:91], v[152:155], v[176:179], v[88:91]
	v_mfma_f32_16x16x32_bf16 v[76:79], v[128:131], v[194:197], v[76:79]
	v_mfma_f32_16x16x32_bf16 v[72:75], v[152:155], v[194:197], v[72:75]
	v_mfma_f32_16x16x32_bf16 v[124:127], v[132:135], v[164:167], v[124:127]
	v_mfma_f32_16x16x32_bf16 v[120:123], v[156:159], v[164:167], v[120:123]
	v_mfma_f32_16x16x32_bf16 v[108:111], v[132:135], v[172:175], v[108:111]
	v_mfma_f32_16x16x32_bf16 v[104:107], v[156:159], v[172:175], v[104:107]
	v_mfma_f32_16x16x32_bf16 v[92:95], v[132:135], v[190:193], v[92:95]
	v_mfma_f32_16x16x32_bf16 v[88:91], v[156:159], v[190:193], v[88:91]
	v_mfma_f32_16x16x32_bf16 v[76:79], v[132:135], v[198:201], v[76:79]
	v_mfma_f32_16x16x32_bf16 v[72:75], v[156:159], v[198:201], v[72:75]
	s_barrier
	s_add_i32 s81, s84, s85
	v_lshl_add_u64 v[180:181], s[8:9], 0, v[136:137]
	s_mov_b32 m0, s81
	ds_read_b128 v[202:205], v187
	ds_read_b128 v[206:209], v187 offset:1024
	ds_read_b128 v[210:213], v187 offset:2048
	ds_read_b128 v[214:217], v187 offset:3072
	global_load_lds_dwordx4 v[180:181], off
	v_lshl_add_u64 v[218:219], s[8:9], 0, v[138:139]
	s_add_i32 m0, s81, 0x2000
	s_nop 0
	global_load_lds_dwordx4 v[218:219], off
	s_barrier
	s_waitcnt lgkmcnt(0)
	s_waitcnt lgkmcnt(0)
	v_mfma_f32_16x16x32_bf16 v[116:119], v[202:205], v[160:163], v[116:119]
	v_mfma_f32_16x16x32_bf16 v[112:115], v[210:213], v[160:163], v[112:115]
	v_mfma_f32_16x16x32_bf16 v[100:103], v[202:205], v[168:171], v[100:103]
	v_mfma_f32_16x16x32_bf16 v[96:99], v[210:213], v[168:171], v[96:99]
	v_mfma_f32_16x16x32_bf16 v[84:87], v[202:205], v[176:179], v[84:87]
	v_mfma_f32_16x16x32_bf16 v[80:83], v[210:213], v[176:179], v[80:83]
	v_mfma_f32_16x16x32_bf16 v[68:71], v[202:205], v[194:197], v[68:71]
	v_mfma_f32_16x16x32_bf16 v[64:67], v[210:213], v[194:197], v[64:67]
	v_mfma_f32_16x16x32_bf16 v[116:119], v[206:209], v[164:167], v[116:119]
	v_mfma_f32_16x16x32_bf16 v[112:115], v[214:217], v[164:167], v[112:115]
	v_mfma_f32_16x16x32_bf16 v[100:103], v[206:209], v[172:175], v[100:103]
	v_mfma_f32_16x16x32_bf16 v[96:99], v[214:217], v[172:175], v[96:99]
	v_mfma_f32_16x16x32_bf16 v[84:87], v[206:209], v[190:193], v[84:87]
	v_mfma_f32_16x16x32_bf16 v[80:83], v[214:217], v[190:193], v[80:83]
	v_mfma_f32_16x16x32_bf16 v[68:71], v[206:209], v[198:201], v[68:71]
	v_mfma_f32_16x16x32_bf16 v[64:67], v[214:217], v[198:201], v[64:67]
	s_mov_b32 m0, s86
	v_lshl_add_u64 v[220:221], s[10:11], 0, v[136:137]
	s_barrier
	ds_read_b128 v[160:163], v186 offset:16384
	ds_read_b128 v[164:167], v186 offset:17408
	ds_read_b128 v[168:171], v186 offset:18432
	ds_read_b128 v[172:175], v186 offset:19456
	ds_read_b128 v[176:179], v186 offset:20480
	ds_read_b128 v[190:193], v186 offset:21504
	ds_read_b128 v[194:197], v186 offset:22528
	ds_read_b128 v[198:201], v186 offset:23552
	global_load_lds_dwordx4 v[220:221], off
	v_lshl_add_u64 v[222:223], s[10:11], 0, v[138:139]
	s_mov_b32 m0, s87
	s_nop 0
	global_load_lds_dwordx4 v[222:223], off
	s_barrier
	s_waitcnt lgkmcnt(0)
	s_waitcnt lgkmcnt(0)
	v_mfma_f32_16x16x32_bf16 v[60:63], v[128:131], v[160:163], v[60:63]
	v_mfma_f32_16x16x32_bf16 v[56:59], v[152:155], v[160:163], v[56:59]
	v_mfma_f32_16x16x32_bf16 v[44:47], v[128:131], v[168:171], v[44:47]
	v_mfma_f32_16x16x32_bf16 v[40:43], v[152:155], v[168:171], v[40:43]
	v_mfma_f32_16x16x32_bf16 v[28:31], v[128:131], v[176:179], v[28:31]
	v_mfma_f32_16x16x32_bf16 v[24:27], v[152:155], v[176:179], v[24:27]
	v_mfma_f32_16x16x32_bf16 v[12:15], v[128:131], v[194:197], v[12:15]
	v_mfma_f32_16x16x32_bf16 v[8:11], v[152:155], v[194:197], v[8:11]
	v_mfma_f32_16x16x32_bf16 v[60:63], v[132:135], v[164:167], v[60:63]
	v_mfma_f32_16x16x32_bf16 v[56:59], v[156:159], v[164:167], v[56:59]
	v_mfma_f32_16x16x32_bf16 v[44:47], v[132:135], v[172:175], v[44:47]
	v_mfma_f32_16x16x32_bf16 v[40:43], v[156:159], v[172:175], v[40:43]
	v_mfma_f32_16x16x32_bf16 v[28:31], v[132:135], v[190:193], v[28:31]
	v_mfma_f32_16x16x32_bf16 v[24:27], v[156:159], v[190:193], v[24:27]
	v_mfma_f32_16x16x32_bf16 v[12:15], v[132:135], v[198:201], v[12:15]
	v_mfma_f32_16x16x32_bf16 v[8:11], v[156:159], v[198:201], v[8:11]
	s_barrier
; #define PG8_STAGE(bufoff, gbase, voff) do { _Pragma("unroll") for (int _i = 0; _i < 2; ++_i) \
;         __builtin_amdgcn_global_load_lds((const unsigned*)((const char*)(gbase) + (voff)[_i]), (LAS unsigned*)(lds + (bufoff) + ldsw + _i * 8192), 16, 0, 0); } while (0)
; #define PG8_LDA(dst, b, h) do { _Pragma("unroll") for (int m = 0; m < 4; ++m) _Pragma("unroll") for (int k = 0; k < 2; ++k) dst[m][k] = *(const LAS bf16x8*)(lds + PG8_SA(b, h) + aoff + m * 2048 + k * 1024); } while (0)
; #define PG8_LDB(dst, b, h) do { _Pragma("unroll") for (int n = 0; n < 2; ++n) _Pragma("unroll") for (int k = 0; k < 2; ++k) dst[n][k] = *(const LAS bf16x8*)(lds + PG8_SB(b, h) + boff + n * 2048 + k * 1024); } while (0)
; #define PG8_MMA(ai, bj, At, Bt) do { __builtin_amdgcn_s_setprio(1); _Pragma("unroll") for (int m = 0; m < 4; ++m) _Pragma("unroll") for (int n = 0; n < 2; ++n) _Pragma("unroll") for (int k = 0; k < 2; ++k) \
;         acc[ai][bj][m][n] = __builtin_amdgcn_mfma_f32_16x16x32_bf16(Bt[n][k], At[m][k], acc[ai][bj][m][n], 0, 0, 0); __builtin_amdgcn_s_setprio(0); } while (0)
; #define PG8_WAIT_V(n) asm volatile("s_waitcnt vmcnt(" #n ")" ::: "memory")
; #define PG8_WAIT_L(n) asm volatile("s_waitcnt lgkmcnt(" #n ")" ::: "memory")
; #define PG8_BAR __builtin_amdgcn_s_barrier()
; #define PG8_SCHED __builtin_amdgcn_sched_barrier(0)
; template <class Epi>
; __device__ __forceinline__ void gemm_phase(LAS unsigned char* lds, const Gemm g, const StaticOrder& S, const Epi& E, float* smem = nullptr) {
;     ...
;             PG8_WAIT_V(6); PG8_BAR; PG8_MMA(1, 1, At, B1); PG8_BAR;
;             PG8_LDB(B0, 1, 0); PG8_SCHED; PG8_LDA(At, 1, 0); PG8_STAGE(PG8_SA(0, 1), a2 + hstep, voffA);
;             PG8_WAIT_L(8); PG8_BAR; PG8_WAIT_L(0); PG8_MMA(0, 0, At, B0); PG8_BAR; PG8_SCHED;
;             PG8_LDB(B1, 1, 1); PG8_STAGE(PG8_SB(1, 0), b3, voffA);
;             PG8_BAR; PG8_WAIT_L(0); PG8_MMA(0, 1, At, B1); PG8_BAR;
;             PG8_LDA(At, 1, 1); PG8_STAGE(PG8_SA(1, 0), a3, voffA);
	s_add_u32 s82, s8, 0x40000
	s_addc_u32 s83, s9, 0
	s_add_i32 s81, s33, s85
	v_lshl_add_u64 v[128:129], s[82:83], 0, v[136:137]
	s_mov_b32 m0, s81
	s_nop 0
	global_load_lds_dwordx4 v[128:129], off
	v_lshl_add_u64 v[128:129], s[82:83], 0, v[138:139]
	s_add_i32 m0, s81, 0x2000
	s_nop 0
	global_load_lds_dwordx4 v[128:129], off
	s_waitcnt vmcnt(6)
	s_barrier
	v_mfma_f32_16x16x32_bf16 v[52:55], v[202:205], v[160:163], v[52:55]
	v_mfma_f32_16x16x32_bf16 v[48:51], v[210:213], v[160:163], v[48:51]
	v_mfma_f32_16x16x32_bf16 v[36:39], v[202:205], v[168:171], v[36:39]
	v_mfma_f32_16x16x32_bf16 v[32:35], v[210:213], v[168:171], v[32:35]
	v_mfma_f32_16x16x32_bf16 v[20:23], v[202:205], v[176:179], v[20:23]
	v_mfma_f32_16x16x32_bf16 v[16:19], v[210:213], v[176:179], v[16:19]
	v_mfma_f32_16x16x32_bf16 v[4:7], v[202:205], v[194:197], v[4:7]
	v_mfma_f32_16x16x32_bf16 v[0:3], v[210:213], v[194:197], v[0:3]
	v_mfma_f32_16x16x32_bf16 v[52:55], v[206:209], v[164:167], v[52:55]
	v_mfma_f32_16x16x32_bf16 v[48:51], v[214:217], v[164:167], v[48:51]
	v_mfma_f32_16x16x32_bf16 v[36:39], v[206:209], v[172:175], v[36:39]
	v_mfma_f32_16x16x32_bf16 v[32:35], v[214:217], v[172:175], v[32:35]
	v_mfma_f32_16x16x32_bf16 v[20:23], v[206:209], v[190:193], v[20:23]
	v_mfma_f32_16x16x32_bf16 v[16:19], v[214:217], v[190:193], v[16:19]
	v_mfma_f32_16x16x32_bf16 v[4:7], v[206:209], v[198:201], v[4:7]
	v_mfma_f32_16x16x32_bf16 v[0:3], v[214:217], v[198:201], v[0:3]
	s_add_i32 s81, 16, 0x18000
	v_add_u32_e32 v140, s81, v182
	s_barrier
	ds_read_b128 v[128:131], v140
	ds_read_b128 v[132:135], v140 offset:1024
	ds_read_b128 v[152:155], v140 offset:2048
	ds_read_b128 v[156:159], v140 offset:3072
	s_add_u32 s10, s10, 0x40000
	s_addc_u32 s11, s11, 0
	s_mov_b32 m0, s88
	v_lshl_add_u64 v[202:203], s[10:11], 0, v[136:137]
	ds_read_b128 v[160:163], v186 offset:32768
	ds_read_b128 v[164:167], v186 offset:33792
	ds_read_b128 v[168:171], v186 offset:34816
	ds_read_b128 v[172:175], v186 offset:35840
	ds_read_b128 v[176:179], v186 offset:36864
	ds_read_b128 v[190:193], v186 offset:37888
	ds_read_b128 v[194:197], v186 offset:38912
	ds_read_b128 v[198:201], v186 offset:39936
	global_load_lds_dwordx4 v[202:203], off
	v_lshl_add_u64 v[202:203], s[10:11], 0, v[138:139]
	s_mov_b32 m0, s89
	s_nop 0
	global_load_lds_dwordx4 v[202:203], off
	s_waitcnt lgkmcnt(8)
	s_barrier
	s_waitcnt lgkmcnt(0)
	s_waitcnt lgkmcnt(0)
	v_mfma_f32_16x16x32_bf16 v[124:127], v[128:131], v[160:163], v[124:127]
	v_mfma_f32_16x16x32_bf16 v[120:123], v[152:155], v[160:163], v[120:123]
	v_mfma_f32_16x16x32_bf16 v[108:111], v[128:131], v[168:171], v[108:111]
	v_mfma_f32_16x16x32_bf16 v[104:107], v[152:155], v[168:171], v[104:107]
	v_mfma_f32_16x16x32_bf16 v[92:95], v[128:131], v[176:179], v[92:95]
	v_mfma_f32_16x16x32_bf16 v[88:91], v[152:155], v[176:179], v[88:91]
	v_mfma_f32_16x16x32_bf16 v[76:79], v[128:131], v[194:197], v[76:79]
	v_mfma_f32_16x16x32_bf16 v[72:75], v[152:155], v[194:197], v[72:75]
	v_mfma_f32_16x16x32_bf16 v[124:127], v[132:135], v[164:167], v[124:127]
	v_mfma_f32_16x16x32_bf16 v[120:123], v[156:159], v[164:167], v[120:123]
	v_mfma_f32_16x16x32_bf16 v[108:111], v[132:135], v[172:175], v[108:111]
	v_mfma_f32_16x16x32_bf16 v[104:107], v[156:159], v[172:175], v[104:107]
	v_mfma_f32_16x16x32_bf16 v[92:95], v[132:135], v[190:193], v[92:95]
	v_mfma_f32_16x16x32_bf16 v[88:91], v[156:159], v[190:193], v[88:91]
	v_mfma_f32_16x16x32_bf16 v[76:79], v[132:135], v[198:201], v[76:79]
	v_mfma_f32_16x16x32_bf16 v[72:75], v[156:159], v[198:201], v[72:75]
	s_barrier
	s_add_i32 s10, 16, 0x1c000
	s_add_i32 s11, s81, s85
	v_add_u32_e32 v140, s10, v182
	v_lshl_add_u64 v[180:181], v[180:181], 0, s[52:53]
	s_mov_b32 m0, s11
	ds_read_b128 v[202:205], v140
	ds_read_b128 v[206:209], v140 offset:1024
	ds_read_b128 v[210:213], v140 offset:2048
	ds_read_b128 v[214:217], v140 offset:3072
	global_load_lds_dwordx4 v[180:181], off
	v_lshl_add_u64 v[180:181], v[218:219], 0, s[52:53]
	s_add_i32 m0, s11, 0x2000
	s_nop 0
	global_load_lds_dwordx4 v[180:181], off
	s_barrier
	s_waitcnt lgkmcnt(0)
	s_waitcnt lgkmcnt(0)
	v_mfma_f32_16x16x32_bf16 v[116:119], v[202:205], v[160:163], v[116:119]
	v_mfma_f32_16x16x32_bf16 v[112:115], v[210:213], v[160:163], v[112:115]
	v_mfma_f32_16x16x32_bf16 v[100:103], v[202:205], v[168:171], v[100:103]
	v_mfma_f32_16x16x32_bf16 v[96:99], v[210:213], v[168:171], v[96:99]
	v_mfma_f32_16x16x32_bf16 v[84:87], v[202:205], v[176:179], v[84:87]
	v_mfma_f32_16x16x32_bf16 v[80:83], v[210:213], v[176:179], v[80:83]
	v_mfma_f32_16x16x32_bf16 v[68:71], v[202:205], v[194:197], v[68:71]
	v_mfma_f32_16x16x32_bf16 v[64:67], v[210:213], v[194:197], v[64:67]
	v_mfma_f32_16x16x32_bf16 v[116:119], v[206:209], v[164:167], v[116:119]
	v_mfma_f32_16x16x32_bf16 v[112:115], v[214:217], v[164:167], v[112:115]
	v_mfma_f32_16x16x32_bf16 v[100:103], v[206:209], v[172:175], v[100:103]
	v_mfma_f32_16x16x32_bf16 v[96:99], v[214:217], v[172:175], v[96:99]
	v_mfma_f32_16x16x32_bf16 v[84:87], v[206:209], v[190:193], v[84:87]
	v_mfma_f32_16x16x32_bf16 v[80:83], v[214:217], v[190:193], v[80:83]
	v_mfma_f32_16x16x32_bf16 v[68:71], v[206:209], v[198:201], v[68:71]
	v_mfma_f32_16x16x32_bf16 v[64:67], v[214:217], v[198:201], v[64:67]
	s_mov_b32 m0, s96
	v_lshl_add_u64 v[180:181], v[220:221], 0, s[52:53]
	s_barrier
;     __device__ __forceinline__ void row(const f32x4 (&a)[2][2], int row, int pn, int wc, int fq) const {
;         if (pn < 2 || pn == 4 || pn == 5) {
;             bf16_t* dst = (pn < 2 ? pU : pBG) + (size_t)row * 512 + (pn & 1) * 256 + wc * 32 + 8 * fq;
; #pragma unroll
;             for (int bj = 0; bj < 2; ++bj) { f32x4 v0 = a[bj][0], v1 = a[bj][1];
;                 if (pn < 2) {
; #pragma unroll
;                     for (int j = 0; j < 4; ++j) { v0[j] = gelu_tanh(v0[j]); v1[j] = gelu_tanh(v1[j]); } }
;                 st_bf16x8(dst + bj * HALF, v0, v1); }
;         } else if (pn < 4) {
;             const int head = (pn - 2) * 4 + wc;
;             f32x4 g[2][2]; float ss = 0.f;
; #pragma unroll
;             for (int bj = 0; bj < 2; ++bj)
; #pragma unroll
;                 for (int n = 0; n < 2; ++n)
; #pragma unroll
;                     for (int j = 0; j < 4; ++j) { const float t = gelu_tanh(a[bj][n][j]); g[bj][n][j] = t; ss += t * t; }
;             ss += __shfl_xor(ss, 16); ss += __shfl_xor(ss, 32);
;             const float rs = rsqrtf(ss * (1.f / 64.f) + EPS);
; #pragma unroll
;             for (int bj = 0; bj < 2; ++bj) { const int d = head * 64 + bj * 32 + 8 * fq;
;                 const f32x4 v0 = g[bj][0] * rs * *(const f32x4*)(g_v + d), v1 = g[bj][1] * rs * *(const f32x4*)(g_v + d + 4);
;                 st_bf16x8(pV + (size_t)row * 512 + d, v0, v1);
;                 if (row >= NP && row < NTOK) { float* o = out + O_VS + (size_t)(row - NP) * 512 + d; *(f32x4*)o = v0; *(f32x4*)(o + 4) = v1; } }
;         } else {
;             const int c = (pn - 6) * 128 + wc * 32 + 8 * fq;
;             const f32x4 z0 = a[0][0] * a[1][0], z1 = a[0][1] * a[1][1];
;             st_bf16x8(pZ + (size_t)row * 512 + c, z0, z1);
;             float* o = nullptr;
;             if (row < NP) { const int t = row & 2047; if (t >= 2046) o = out + O_CONVP + (size_t)((row >> 11) * 2 + (t - 2046)) * 512 + c; }
; template <class Epi>
; __device__ __forceinline__ void gemm_phase(LAS unsigned char* lds, const Gemm g, const StaticOrder& S, const Epi& E, float* smem = nullptr) {
;     ...
;             PG8_LDA(At, 1, 1); PG8_STAGE(PG8_SA(1, 0), a3, voffA);
;             PG8_BAR; PG8_WAIT_L(0); PG8_MMA(1, 0, At, B0); PG8_BAR; PG8_SCHED;
;             PG8_STAGE(PG8_SB(1, 1), b3 + hstep, voffA);
;             PG8_WAIT_V(6); PG8_BAR; PG8_MMA(1, 1, At, B1); PG8_BAR;
	ds_read_b128 v[160:163], v186 offset:49152
	ds_read_b128 v[164:167], v186 offset:50176
	ds_read_b128 v[168:171], v186 offset:51200
	ds_read_b128 v[172:175], v186 offset:52224
	ds_read_b128 v[176:179], v186 offset:53248
	ds_read_b128 v[190:193], v186 offset:54272
	ds_read_b128 v[194:197], v186 offset:55296
	ds_read_b128 v[198:201], v186 offset:56320
	global_load_lds_dwordx4 v[180:181], off
	v_lshl_add_u64 v[180:181], v[222:223], 0, s[52:53]
	s_mov_b32 m0, s97
	s_nop 0
	global_load_lds_dwordx4 v[180:181], off
	s_barrier
	s_waitcnt lgkmcnt(0)
	s_waitcnt lgkmcnt(0)
	v_mfma_f32_16x16x32_bf16 v[60:63], v[128:131], v[160:163], v[60:63]
	v_mfma_f32_16x16x32_bf16 v[56:59], v[152:155], v[160:163], v[56:59]
	v_mfma_f32_16x16x32_bf16 v[44:47], v[128:131], v[168:171], v[44:47]
	v_mfma_f32_16x16x32_bf16 v[40:43], v[152:155], v[168:171], v[40:43]
	v_mfma_f32_16x16x32_bf16 v[28:31], v[128:131], v[176:179], v[28:31]
	v_mfma_f32_16x16x32_bf16 v[24:27], v[152:155], v[176:179], v[24:27]
	v_mfma_f32_16x16x32_bf16 v[12:15], v[128:131], v[194:197], v[12:15]
	v_mfma_f32_16x16x32_bf16 v[8:11], v[152:155], v[194:197], v[8:11]
	v_mfma_f32_16x16x32_bf16 v[60:63], v[132:135], v[164:167], v[60:63]
	v_mfma_f32_16x16x32_bf16 v[56:59], v[156:159], v[164:167], v[56:59]
	v_mfma_f32_16x16x32_bf16 v[44:47], v[132:135], v[172:175], v[44:47]
	v_mfma_f32_16x16x32_bf16 v[40:43], v[156:159], v[172:175], v[40:43]
	v_mfma_f32_16x16x32_bf16 v[28:31], v[132:135], v[190:193], v[28:31]
	v_mfma_f32_16x16x32_bf16 v[24:27], v[156:159], v[190:193], v[24:27]
	v_mfma_f32_16x16x32_bf16 v[12:15], v[132:135], v[198:201], v[12:15]
	v_mfma_f32_16x16x32_bf16 v[8:11], v[156:159], v[198:201], v[8:11]
	s_barrier
	s_add_u32 s8, s8, 0x40080
	s_addc_u32 s9, s9, 0
	s_add_i32 s10, s10, s85
	v_lshl_add_u64 v[128:129], s[8:9], 0, v[136:137]
	s_mov_b32 m0, s10
	s_nop 0
	global_load_lds_dwordx4 v[128:129], off
	v_lshl_add_u64 v[128:129], s[8:9], 0, v[138:139]
	s_add_i32 m0, s10, 0x2000
	s_nop 0
	global_load_lds_dwordx4 v[128:129], off
	s_waitcnt vmcnt(6)
	s_barrier
	v_mfma_f32_16x16x32_bf16 v[52:55], v[202:205], v[160:163], v[52:55]
	v_mfma_f32_16x16x32_bf16 v[48:51], v[210:213], v[160:163], v[48:51]
	v_mfma_f32_16x16x32_bf16 v[36:39], v[202:205], v[168:171], v[36:39]
	v_mfma_f32_16x16x32_bf16 v[32:35], v[210:213], v[168:171], v[32:35]
	v_mfma_f32_16x16x32_bf16 v[20:23], v[202:205], v[176:179], v[20:23]
	v_mfma_f32_16x16x32_bf16 v[16:19], v[210:213], v[176:179], v[16:19]
	v_mfma_f32_16x16x32_bf16 v[4:7], v[202:205], v[194:197], v[4:7]
	v_mfma_f32_16x16x32_bf16 v[0:3], v[210:213], v[194:197], v[0:3]
	v_mfma_f32_16x16x32_bf16 v[52:55], v[206:209], v[164:167], v[52:55]
	v_mfma_f32_16x16x32_bf16 v[48:51], v[214:217], v[164:167], v[48:51]
	v_mfma_f32_16x16x32_bf16 v[36:39], v[206:209], v[172:175], v[36:39]
	v_mfma_f32_16x16x32_bf16 v[32:35], v[214:217], v[172:175], v[32:35]
	v_mfma_f32_16x16x32_bf16 v[20:23], v[206:209], v[190:193], v[20:23]
	v_mfma_f32_16x16x32_bf16 v[16:19], v[214:217], v[190:193], v[16:19]
	v_mfma_f32_16x16x32_bf16 v[4:7], v[206:209], v[198:201], v[4:7]
	v_mfma_f32_16x16x32_bf16 v[0:3], v[214:217], v[198:201], v[0:3]
	s_add_i32 s80, s80, 2
	s_add_u32 s6, s6, 0x100
	s_addc_u32 s7, s7, 0
	s_add_u32 s73, s73, 0x100
	s_addc_u32 s75, s75, 0
	s_cmp_gt_u32 s80, 13
	s_barrier
	s_cbranch_scc0 .LBB0_212
	s_lshl_b32 s73, s4, 8
	s_add_i32 s73, s73, s90
	s_cmp_lt_i32 s0, 2
	s_cselect_b64 s[80:81], -1, 0
	s_cmp_gt_i32 s0, 1
	s_cselect_b64 s[4:5], -1, 0
	s_and_b32 s1, s0, -2
	s_cmp_lg_u32 s1, 4
	s_cselect_b64 s[6:7], -1, 0
	s_and_b64 s[6:7], s[4:5], s[6:7]
	s_cmp_gt_u32 s0, 3
	s_cselect_b64 s[82:83], -1, 0
	s_lshl_b32 s4, s0, 8
	s_and_b32 s75, s73, 0xffffff80
	v_lshl_add_u32 v154, s0, 7, v183
	v_add_u32_e32 v140, s4, v184
	s_cmpk_eq_i32 s75, 0x4000
	v_or_b32_e32 v156, s73, v143
	v_ashrrev_i32_e32 v155, 31, v154
	v_or_b32_e32 v152, 32, v140
	v_mov_b32_e32 v153, v141
	s_mov_b64 s[0:1], -1
	s_cselect_b64 s[10:11], -1, 0
	s_and_b64 vcc, exec, s[6:7]
	s_cbranch_vccz .LBB0_224
	s_and_b64 vcc, exec, s[82:83]
	s_cbranch_vccz .LBB0_218
	v_ashrrev_i32_e32 v157, 31, v156
	v_lshlrev_b64 v[158:159], 10, v[156:157]
	s_cmpk_lt_u32 s73, 0x4080
	v_lshl_add_u64 v[158:159], s[50:51], 0, v[158:159]
	v_cmp_lt_i32_e32 vcc, s12, v156
	s_cselect_b64 s[0:1], -1, 0
	v_pk_mul_f32 v[130:131], v[126:127], v[118:119]
	v_pk_mul_f32 v[128:129], v[124:125], v[116:117]
	v_pk_mul_f32 v[134:135], v[122:123], v[114:115]
	v_pk_mul_f32 v[132:133], v[120:121], v[112:113]
	v_lshl_add_u64 v[162:163], v[154:155], 1, v[158:159]
	s_and_b64 s[8:9], s[0:1], vcc
	v_cvt_pk_bf16_f32 v158, v128, v129
	v_cvt_pk_bf16_f32 v159, v130, v131
	v_cvt_pk_bf16_f32 v160, v132, v133
	v_cvt_pk_bf16_f32 v161, v134, v135
	global_store_dwordx4 v[162:163], v[158:161], off
	s_and_saveexec_b64 s[0:1], s[8:9]
	s_cbranch_execz .LBB0_217
	v_lshl_add_u32 v158, v156, 1, v189
	v_mov_b32_e32 v159, v141
	v_lshlrev_b64 v[158:159], 11, v[158:159]
	v_lshl_add_u64 v[158:159], s[66:67], 0, v[158:159]
	v_lshl_add_u64 v[158:159], v[154:155], 2, v[158:159]
	global_store_dwordx4 v[158:159], v[128:131], off
	global_store_dwordx4 v[158:159], v[132:135], off offset:16

; #define PG8_STAGE(bufoff, gbase, voff) do { _Pragma("unroll") for (int _i = 0; _i < 2; ++_i) \
;         __builtin_amdgcn_global_load_lds((const unsigned*)((const char*)(gbase) + (voff)[_i]), (LAS unsigned*)(lds + (bufoff) + ldsw + _i * 8192), 16, 0, 0); } while (0)
; #define PG8_LDA(dst, b, h) do { _Pragma("unroll") for (int m = 0; m < 4; ++m) _Pragma("unroll") for (int k = 0; k < 2; ++k) dst[m][k] = *(const LAS bf16x8*)(lds + PG8_SA(b, h) + aoff + m * 2048 + k * 1024); } while (0)
; #define PG8_LDB(dst, b, h) do { _Pragma("unroll") for (int n = 0; n < 2; ++n) _Pragma("unroll") for (int k = 0; k < 2; ++k) dst[n][k] = *(const LAS bf16x8*)(lds + PG8_SB(b, h) + boff + n * 2048 + k * 1024); } while (0)
; #define PG8_MMA(ai, bj, At, Bt) do { __builtin_amdgcn_s_setprio(1); _Pragma("unroll") for (int m = 0; m < 4; ++m) _Pragma("unroll") for (int n = 0; n < 2; ++n) _Pragma("unroll") for (int k = 0; k < 2; ++k) \
;         acc[ai][bj][m][n] = __builtin_amdgcn_mfma_f32_16x16x32_bf16(Bt[n][k], At[m][k], acc[ai][bj][m][n], 0, 0, 0); __builtin_amdgcn_s_setprio(0); } while (0)
; #define PG8_WAIT_V(n) asm volatile("s_waitcnt vmcnt(" #n ")" ::: "memory")
; #define PG8_WAIT_L(n) asm volatile("s_waitcnt lgkmcnt(" #n ")" ::: "memory")
; #define PG8_BAR __builtin_amdgcn_s_barrier()
; #define PG8_SCHED __builtin_amdgcn_sched_barrier(0)
; template <class Epi>
; __device__ __forceinline__ void gemm_phase(LAS unsigned char* lds, const Gemm g, const StaticOrder& S, const Epi& E, float* smem = nullptr) {
;     ...
;             PG8_LDB(B0, 0, 0); PG8_SCHED; PG8_LDA(At, 0, 0); PG8_STAGE(PG8_SA(1, 1), a1 + hstep, voffA);
;             PG8_WAIT_L(8); PG8_BAR; PG8_WAIT_L(0); PG8_MMA(0, 0, At, B0); PG8_BAR; PG8_SCHED;
;             PG8_LDB(B1, 0, 1); PG8_STAGE(PG8_SB(0, 0), b2, voffA);
;             PG8_BAR; PG8_WAIT_L(0); PG8_MMA(0, 1, At, B1); PG8_BAR;
;             PG8_LDA(At, 0, 1); PG8_STAGE(PG8_SA(0, 0), a2, voffA);
;             PG8_BAR; PG8_WAIT_L(0); PG8_MMA(1, 0, At, B0); PG8_BAR; PG8_SCHED;
;             PG8_STAGE(PG8_SB(0, 1), b2 + hstep, voffA);
;             PG8_WAIT_V(6); PG8_BAR; PG8_MMA(1, 1, At, B1); PG8_BAR;
.LBB0_528:
	v_add_u32_e32 v158, s72, v144
	s_add_u32 s52, s20, s50
	ds_read_b128 v[146:149], v158
	ds_read_b128 v[150:153], v158 offset:1024
	ds_read_b128 v[154:157], v158 offset:2048
	ds_read_b128 v[158:161], v158 offset:3072
	s_addc_u32 s53, s21, s51
	s_add_u32 s52, s52, 0x100
	s_addc_u32 s53, s53, 0
	s_add_u32 s80, s75, s50
	s_addc_u32 s81, s76, s51
	s_cmpk_eq_i32 s50, 0x700
	s_cselect_b32 s65, s45, s53
	s_cselect_b32 s64, s77, s52
	s_cselect_b32 s53, s25, s81
	s_cselect_b32 s52, s78, s80
	v_lshl_add_u64 v[194:195], v[140:141], 0, s[50:51]
	s_add_i32 m0, s61, 0xc000
	ds_read_b128 v[162:165], v145
	ds_read_b128 v[166:169], v145 offset:1024
	ds_read_b128 v[170:173], v145 offset:2048
	ds_read_b128 v[174:177], v145 offset:3072
	ds_read_b128 v[178:181], v145 offset:4096
	ds_read_b128 v[182:185], v145 offset:5120
	ds_read_b128 v[186:189], v145 offset:6144
	ds_read_b128 v[190:193], v145 offset:7168
	global_load_lds_dwordx4 v[194:195], off
	v_lshl_add_u64 v[194:195], v[142:143], 0, s[50:51]
	s_add_i32 m0, s61, 0xe000
	s_nop 0
	global_load_lds_dwordx4 v[194:195], off
	s_waitcnt lgkmcnt(8)
	s_barrier
	s_waitcnt lgkmcnt(0)
	s_waitcnt lgkmcnt(0)
	v_mfma_f32_16x16x32_bf16 v[124:127], v[146:149], v[162:165], v[124:127]
	v_mfma_f32_16x16x32_bf16 v[120:123], v[154:157], v[162:165], v[120:123]
	v_mfma_f32_16x16x32_bf16 v[112:115], v[146:149], v[170:173], v[112:115]
	v_mfma_f32_16x16x32_bf16 v[104:107], v[154:157], v[170:173], v[104:107]
	v_mfma_f32_16x16x32_bf16 v[96:99], v[146:149], v[178:181], v[96:99]
	v_mfma_f32_16x16x32_bf16 v[88:91], v[154:157], v[178:181], v[88:91]
	v_mfma_f32_16x16x32_bf16 v[80:83], v[146:149], v[186:189], v[80:83]
	v_mfma_f32_16x16x32_bf16 v[72:75], v[154:157], v[186:189], v[72:75]
	v_mfma_f32_16x16x32_bf16 v[124:127], v[150:153], v[166:169], v[124:127]
	v_mfma_f32_16x16x32_bf16 v[120:123], v[158:161], v[166:169], v[120:123]
	v_mfma_f32_16x16x32_bf16 v[112:115], v[150:153], v[174:177], v[112:115]
	v_mfma_f32_16x16x32_bf16 v[104:107], v[158:161], v[174:177], v[104:107]
	v_mfma_f32_16x16x32_bf16 v[96:99], v[150:153], v[182:185], v[96:99]
	v_mfma_f32_16x16x32_bf16 v[88:91], v[158:161], v[182:185], v[88:91]
	v_mfma_f32_16x16x32_bf16 v[80:83], v[150:153], v[190:193], v[80:83]
	v_mfma_f32_16x16x32_bf16 v[72:75], v[158:161], v[190:193], v[72:75]
	s_barrier
	v_add_u32_e32 v194, s73, v144
	s_add_i32 s80, s72, s60
	ds_read_b128 v[198:201], v194
	ds_read_b128 v[202:205], v194 offset:1024
	ds_read_b128 v[206:209], v194 offset:2048
	ds_read_b128 v[210:213], v194 offset:3072
	v_lshl_add_u64 v[194:195], s[52:53], 0, v[128:129]
	s_mov_b32 m0, s80
	v_lshl_add_u64 v[214:215], s[52:53], 0, v[130:131]
	global_load_lds_dwordx4 v[194:195], off
	s_add_i32 m0, s80, 0x2000
	s_nop 0
	global_load_lds_dwordx4 v[214:215], off
	s_barrier
	s_waitcnt lgkmcnt(0)
	s_waitcnt lgkmcnt(0)
	v_mfma_f32_16x16x32_bf16 v[116:119], v[198:201], v[162:165], v[116:119]
	v_mfma_f32_16x16x32_bf16 v[108:111], v[206:209], v[162:165], v[108:111]
	v_mfma_f32_16x16x32_bf16 v[100:103], v[198:201], v[170:173], v[100:103]
	v_mfma_f32_16x16x32_bf16 v[92:95], v[206:209], v[170:173], v[92:95]
	v_mfma_f32_16x16x32_bf16 v[84:87], v[198:201], v[178:181], v[84:87]
	v_mfma_f32_16x16x32_bf16 v[76:79], v[206:209], v[178:181], v[76:79]
	v_mfma_f32_16x16x32_bf16 v[68:71], v[198:201], v[186:189], v[68:71]
	v_mfma_f32_16x16x32_bf16 v[64:67], v[206:209], v[186:189], v[64:67]
	v_mfma_f32_16x16x32_bf16 v[116:119], v[202:205], v[166:169], v[116:119]
	v_mfma_f32_16x16x32_bf16 v[108:111], v[210:213], v[166:169], v[108:111]
	v_mfma_f32_16x16x32_bf16 v[100:103], v[202:205], v[174:177], v[100:103]
	v_mfma_f32_16x16x32_bf16 v[92:95], v[210:213], v[174:177], v[92:95]
	v_mfma_f32_16x16x32_bf16 v[84:87], v[202:205], v[182:185], v[84:87]
	v_mfma_f32_16x16x32_bf16 v[76:79], v[210:213], v[182:185], v[76:79]
	v_mfma_f32_16x16x32_bf16 v[68:71], v[202:205], v[190:193], v[68:71]
	v_mfma_f32_16x16x32_bf16 v[64:67], v[210:213], v[190:193], v[64:67]
	s_mov_b32 m0, s61
	v_lshl_add_u64 v[216:217], s[64:65], 0, v[128:129]
	s_barrier
	ds_read_b128 v[162:165], v145 offset:16384
	ds_read_b128 v[166:169], v145 offset:17408
	ds_read_b128 v[170:173], v145 offset:18432
	ds_read_b128 v[174:177], v145 offset:19456
	ds_read_b128 v[178:181], v145 offset:20480
	ds_read_b128 v[182:185], v145 offset:21504
	ds_read_b128 v[186:189], v145 offset:22528
	ds_read_b128 v[190:193], v145 offset:23552
	global_load_lds_dwordx4 v[216:217], off
	v_lshl_add_u64 v[218:219], s[64:65], 0, v[130:131]
	s_mov_b32 m0, s66
	s_nop 0
	global_load_lds_dwordx4 v[218:219], off
	s_barrier
	s_waitcnt lgkmcnt(0)
	s_waitcnt lgkmcnt(0)
	v_mfma_f32_16x16x32_bf16 v[60:63], v[146:149], v[162:165], v[60:63]
	v_mfma_f32_16x16x32_bf16 v[56:59], v[154:157], v[162:165], v[56:59]
	v_mfma_f32_16x16x32_bf16 v[48:51], v[146:149], v[170:173], v[48:51]
	v_mfma_f32_16x16x32_bf16 v[40:43], v[154:157], v[170:173], v[40:43]
	v_mfma_f32_16x16x32_bf16 v[32:35], v[146:149], v[178:181], v[32:35]
	v_mfma_f32_16x16x32_bf16 v[24:27], v[154:157], v[178:181], v[24:27]
	v_mfma_f32_16x16x32_bf16 v[16:19], v[146:149], v[186:189], v[16:19]
	v_mfma_f32_16x16x32_bf16 v[8:11], v[154:157], v[186:189], v[8:11]
	v_mfma_f32_16x16x32_bf16 v[60:63], v[150:153], v[166:169], v[60:63]
	v_mfma_f32_16x16x32_bf16 v[56:59], v[158:161], v[166:169], v[56:59]
	v_mfma_f32_16x16x32_bf16 v[48:51], v[150:153], v[174:177], v[48:51]
	v_mfma_f32_16x16x32_bf16 v[40:43], v[158:161], v[174:177], v[40:43]
	v_mfma_f32_16x16x32_bf16 v[32:35], v[150:153], v[182:185], v[32:35]
	v_mfma_f32_16x16x32_bf16 v[24:27], v[158:161], v[182:185], v[24:27]
	v_mfma_f32_16x16x32_bf16 v[16:19], v[150:153], v[190:193], v[16:19]
	v_mfma_f32_16x16x32_bf16 v[8:11], v[158:161], v[190:193], v[8:11]
	s_barrier
; #define PG8_STAGE(bufoff, gbase, voff) do { _Pragma("unroll") for (int _i = 0; _i < 2; ++_i) \
;         __builtin_amdgcn_global_load_lds((const unsigned*)((const char*)(gbase) + (voff)[_i]), (LAS unsigned*)(lds + (bufoff) + ldsw + _i * 8192), 16, 0, 0); } while (0)
; #define PG8_LDA(dst, b, h) do { _Pragma("unroll") for (int m = 0; m < 4; ++m) _Pragma("unroll") for (int k = 0; k < 2; ++k) dst[m][k] = *(const LAS bf16x8*)(lds + PG8_SA(b, h) + aoff + m * 2048 + k * 1024); } while (0)
; #define PG8_LDB(dst, b, h) do { _Pragma("unroll") for (int n = 0; n < 2; ++n) _Pragma("unroll") for (int k = 0; k < 2; ++k) dst[n][k] = *(const LAS bf16x8*)(lds + PG8_SB(b, h) + boff + n * 2048 + k * 1024); } while (0)
; #define PG8_MMA(ai, bj, At, Bt) do { __builtin_amdgcn_s_setprio(1); _Pragma("unroll") for (int m = 0; m < 4; ++m) _Pragma("unroll") for (int n = 0; n < 2; ++n) _Pragma("unroll") for (int k = 0; k < 2; ++k) \
;         acc[ai][bj][m][n] = __builtin_amdgcn_mfma_f32_16x16x32_bf16(Bt[n][k], At[m][k], acc[ai][bj][m][n], 0, 0, 0); __builtin_amdgcn_s_setprio(0); } while (0)
; #define PG8_WAIT_V(n) asm volatile("s_waitcnt vmcnt(" #n ")" ::: "memory")
; #define PG8_WAIT_L(n) asm volatile("s_waitcnt lgkmcnt(" #n ")" ::: "memory")
; #define PG8_BAR __builtin_amdgcn_s_barrier()
; #define PG8_SCHED __builtin_amdgcn_sched_barrier(0)
; template <class Epi>
; __device__ __forceinline__ void gemm_phase(LAS unsigned char* lds, const Gemm g, const StaticOrder& S, const Epi& E, float* smem = nullptr) {
;     ...
;             PG8_WAIT_V(6); PG8_BAR; PG8_MMA(1, 1, At, B1); PG8_BAR;
;             PG8_LDB(B0, 1, 0); PG8_SCHED; PG8_LDA(At, 1, 0); PG8_STAGE(PG8_SA(0, 1), a2 + hstep, voffA);
;             PG8_WAIT_L(8); PG8_BAR; PG8_WAIT_L(0); PG8_MMA(0, 0, At, B0); PG8_BAR; PG8_SCHED;
;             PG8_LDB(B1, 1, 1); PG8_STAGE(PG8_SB(1, 0), b3, voffA);
;             PG8_BAR; PG8_WAIT_L(0); PG8_MMA(0, 1, At, B1); PG8_BAR;
;             PG8_LDA(At, 1, 1); PG8_STAGE(PG8_SA(1, 0), a3, voffA);
	s_add_u32 s80, s52, 0x40000
	s_addc_u32 s81, s53, 0
	s_add_i32 s82, s73, s60
	v_lshl_add_u64 v[146:147], s[80:81], 0, v[128:129]
	s_mov_b32 m0, s82
	s_nop 0
	global_load_lds_dwordx4 v[146:147], off
	v_lshl_add_u64 v[146:147], s[80:81], 0, v[130:131]
	s_add_i32 m0, s82, 0x2000
	s_nop 0
	global_load_lds_dwordx4 v[146:147], off
	s_waitcnt vmcnt(6)
	s_barrier
	v_mfma_f32_16x16x32_bf16 v[52:55], v[198:201], v[162:165], v[52:55]
	v_mfma_f32_16x16x32_bf16 v[44:47], v[206:209], v[162:165], v[44:47]
	v_mfma_f32_16x16x32_bf16 v[36:39], v[198:201], v[170:173], v[36:39]
	v_mfma_f32_16x16x32_bf16 v[28:31], v[206:209], v[170:173], v[28:31]
	v_mfma_f32_16x16x32_bf16 v[20:23], v[198:201], v[178:181], v[20:23]
	v_mfma_f32_16x16x32_bf16 v[12:15], v[206:209], v[178:181], v[12:15]
	v_mfma_f32_16x16x32_bf16 v[4:7], v[198:201], v[186:189], v[4:7]
	v_mfma_f32_16x16x32_bf16 v[0:3], v[206:209], v[186:189], v[0:3]
	v_mfma_f32_16x16x32_bf16 v[52:55], v[202:205], v[166:169], v[52:55]
	v_mfma_f32_16x16x32_bf16 v[44:47], v[210:213], v[166:169], v[44:47]
	v_mfma_f32_16x16x32_bf16 v[36:39], v[202:205], v[174:177], v[36:39]
	v_mfma_f32_16x16x32_bf16 v[28:31], v[210:213], v[174:177], v[28:31]
	v_mfma_f32_16x16x32_bf16 v[20:23], v[202:205], v[182:185], v[20:23]
	v_mfma_f32_16x16x32_bf16 v[12:15], v[210:213], v[182:185], v[12:15]
	v_mfma_f32_16x16x32_bf16 v[4:7], v[202:205], v[190:193], v[4:7]
	v_mfma_f32_16x16x32_bf16 v[0:3], v[210:213], v[190:193], v[0:3]
	s_add_i32 s80, 16, 0x18000
	v_add_u32_e32 v158, s80, v144
	s_barrier
	ds_read_b128 v[146:149], v158
	ds_read_b128 v[150:153], v158 offset:1024
	ds_read_b128 v[154:157], v158 offset:2048
	ds_read_b128 v[158:161], v158 offset:3072
	s_add_u32 s64, s64, 0x40000
	s_addc_u32 s65, s65, 0
	s_mov_b32 m0, s67
	v_lshl_add_u64 v[198:199], s[64:65], 0, v[128:129]
	ds_read_b128 v[162:165], v145 offset:32768
	ds_read_b128 v[166:169], v145 offset:33792
	ds_read_b128 v[170:173], v145 offset:34816
	ds_read_b128 v[174:177], v145 offset:35840
	ds_read_b128 v[178:181], v145 offset:36864
	ds_read_b128 v[182:185], v145 offset:37888
	ds_read_b128 v[186:189], v145 offset:38912
	ds_read_b128 v[190:193], v145 offset:39936
	global_load_lds_dwordx4 v[198:199], off
	v_lshl_add_u64 v[198:199], s[64:65], 0, v[130:131]
	s_mov_b32 m0, s68
	s_nop 0
	global_load_lds_dwordx4 v[198:199], off
	s_waitcnt lgkmcnt(8)
	s_barrier
	s_waitcnt lgkmcnt(0)
	s_waitcnt lgkmcnt(0)
	v_mfma_f32_16x16x32_bf16 v[124:127], v[146:149], v[162:165], v[124:127]
	v_mfma_f32_16x16x32_bf16 v[120:123], v[154:157], v[162:165], v[120:123]
	v_mfma_f32_16x16x32_bf16 v[112:115], v[146:149], v[170:173], v[112:115]
	v_mfma_f32_16x16x32_bf16 v[104:107], v[154:157], v[170:173], v[104:107]
	v_mfma_f32_16x16x32_bf16 v[96:99], v[146:149], v[178:181], v[96:99]
	v_mfma_f32_16x16x32_bf16 v[88:91], v[154:157], v[178:181], v[88:91]
	v_mfma_f32_16x16x32_bf16 v[80:83], v[146:149], v[186:189], v[80:83]
	v_mfma_f32_16x16x32_bf16 v[72:75], v[154:157], v[186:189], v[72:75]
	v_mfma_f32_16x16x32_bf16 v[124:127], v[150:153], v[166:169], v[124:127]
	v_mfma_f32_16x16x32_bf16 v[120:123], v[158:161], v[166:169], v[120:123]
	v_mfma_f32_16x16x32_bf16 v[112:115], v[150:153], v[174:177], v[112:115]
	v_mfma_f32_16x16x32_bf16 v[104:107], v[158:161], v[174:177], v[104:107]
	v_mfma_f32_16x16x32_bf16 v[96:99], v[150:153], v[182:185], v[96:99]
	v_mfma_f32_16x16x32_bf16 v[88:91], v[158:161], v[182:185], v[88:91]
	v_mfma_f32_16x16x32_bf16 v[80:83], v[150:153], v[190:193], v[80:83]
	v_mfma_f32_16x16x32_bf16 v[72:75], v[158:161], v[190:193], v[72:75]
	s_barrier
	s_add_i32 s64, 16, 0x1c000
	s_add_i32 s65, s80, s60
	v_add_u32_e32 v197, s64, v144
	v_lshl_add_u64 v[194:195], v[194:195], 0, s[22:23]
	s_mov_b32 m0, s65
	ds_read_b128 v[198:201], v197
	ds_read_b128 v[202:205], v197 offset:1024
	ds_read_b128 v[206:209], v197 offset:2048
	ds_read_b128 v[210:213], v197 offset:3072
	global_load_lds_dwordx4 v[194:195], off
	v_lshl_add_u64 v[194:195], v[214:215], 0, s[22:23]
	s_add_i32 m0, s65, 0x2000
	s_nop 0
	global_load_lds_dwordx4 v[194:195], off
	s_barrier
	s_waitcnt lgkmcnt(0)
	s_waitcnt lgkmcnt(0)
	v_mfma_f32_16x16x32_bf16 v[116:119], v[198:201], v[162:165], v[116:119]
	v_mfma_f32_16x16x32_bf16 v[108:111], v[206:209], v[162:165], v[108:111]
	v_mfma_f32_16x16x32_bf16 v[100:103], v[198:201], v[170:173], v[100:103]
	v_mfma_f32_16x16x32_bf16 v[92:95], v[206:209], v[170:173], v[92:95]
	v_mfma_f32_16x16x32_bf16 v[84:87], v[198:201], v[178:181], v[84:87]
	v_mfma_f32_16x16x32_bf16 v[76:79], v[206:209], v[178:181], v[76:79]
	v_mfma_f32_16x16x32_bf16 v[68:71], v[198:201], v[186:189], v[68:71]
	v_mfma_f32_16x16x32_bf16 v[64:67], v[206:209], v[186:189], v[64:67]
	v_mfma_f32_16x16x32_bf16 v[116:119], v[202:205], v[166:169], v[116:119]
	v_mfma_f32_16x16x32_bf16 v[108:111], v[210:213], v[166:169], v[108:111]
	v_mfma_f32_16x16x32_bf16 v[100:103], v[202:205], v[174:177], v[100:103]
	v_mfma_f32_16x16x32_bf16 v[92:95], v[210:213], v[174:177], v[92:95]
	v_mfma_f32_16x16x32_bf16 v[84:87], v[202:205], v[182:185], v[84:87]
	v_mfma_f32_16x16x32_bf16 v[76:79], v[210:213], v[182:185], v[76:79]
	v_mfma_f32_16x16x32_bf16 v[68:71], v[202:205], v[190:193], v[68:71]
	v_mfma_f32_16x16x32_bf16 v[64:67], v[210:213], v[190:193], v[64:67]
	s_mov_b32 m0, s69
	v_lshl_add_u64 v[194:195], v[216:217], 0, s[22:23]
	s_barrier
	ds_read_b128 v[162:165], v145 offset:49152
	ds_read_b128 v[166:169], v145 offset:50176
	ds_read_b128 v[170:173], v145 offset:51200
	ds_read_b128 v[174:177], v145 offset:52224
	ds_read_b128 v[178:181], v145 offset:53248
	ds_read_b128 v[182:185], v145 offset:54272
	ds_read_b128 v[186:189], v145 offset:55296
	ds_read_b128 v[190:193], v145 offset:56320
	global_load_lds_dwordx4 v[194:195], off
	v_lshl_add_u64 v[194:195], v[218:219], 0, s[22:23]
	s_mov_b32 m0, s70
	s_nop 0
	global_load_lds_dwordx4 v[194:195], off
	s_barrier
; #define PG8_STAGE(bufoff, gbase, voff) do { _Pragma("unroll") for (int _i = 0; _i < 2; ++_i) \
;         __builtin_amdgcn_global_load_lds((const unsigned*)((const char*)(gbase) + (voff)[_i]), (LAS unsigned*)(lds + (bufoff) + ldsw + _i * 8192), 16, 0, 0); } while (0)
; #define PG8_LDA(dst, b, h) do { _Pragma("unroll") for (int m = 0; m < 4; ++m) _Pragma("unroll") for (int k = 0; k < 2; ++k) dst[m][k] = *(const LAS bf16x8*)(lds + PG8_SA(b, h) + aoff + m * 2048 + k * 1024); } while (0)
; #define PG8_MMA(ai, bj, At, Bt) do { __builtin_amdgcn_s_setprio(1); _Pragma("unroll") for (int m = 0; m < 4; ++m) _Pragma("unroll") for (int n = 0; n < 2; ++n) _Pragma("unroll") for (int k = 0; k < 2; ++k) \
;         acc[ai][bj][m][n] = __builtin_amdgcn_mfma_f32_16x16x32_bf16(Bt[n][k], At[m][k], acc[ai][bj][m][n], 0, 0, 0); __builtin_amdgcn_s_setprio(0); } while (0)
; #define PG8_WAIT_V(n) asm volatile("s_waitcnt vmcnt(" #n ")" ::: "memory")
; #define PG8_WAIT_L(n) asm volatile("s_waitcnt lgkmcnt(" #n ")" ::: "memory")
; #define PG8_BAR __builtin_amdgcn_s_barrier()
; #define PG8_SCHED __builtin_amdgcn_sched_barrier(0)
; template <class Epi>
; __device__ __forceinline__ void gemm_phase(LAS unsigned char* lds, const Gemm g, const StaticOrder& S, const Epi& E, float* smem = nullptr) {
;     ...
;             PG8_LDA(At, 1, 1); PG8_STAGE(PG8_SA(1, 0), a3, voffA);
;             PG8_BAR; PG8_WAIT_L(0); PG8_MMA(1, 0, At, B0); PG8_BAR; PG8_SCHED;
;             PG8_STAGE(PG8_SB(1, 1), b3 + hstep, voffA);
;             PG8_WAIT_V(6); PG8_BAR; PG8_MMA(1, 1, At, B1); PG8_BAR;
;         }
;         if constexpr (!Epi::AFTER_DRAIN) E(acc, cur, wr, wc, fr, fq);
;         if (!has_next) break;
; #pragma unroll
;         for (int a = 0; a < 2; ++a)
; #pragma unroll
;             for (int b = 0; b < 2; ++b)
; #pragma unroll
;                 for (int m = 0; m < 4; ++m)
; #pragma unroll
;                     for (int n = 0; n < 2; ++n) acc[a][b][m][n] = (f32x4){0.f, 0.f, 0.f, 0.f};
;         cur = nxt; cA = nA; cB = nB; ++ui;
	s_waitcnt lgkmcnt(0)
	s_waitcnt lgkmcnt(0)
	v_mfma_f32_16x16x32_bf16 v[60:63], v[146:149], v[162:165], v[60:63]
	v_mfma_f32_16x16x32_bf16 v[56:59], v[154:157], v[162:165], v[56:59]
	v_mfma_f32_16x16x32_bf16 v[48:51], v[146:149], v[170:173], v[48:51]
	v_mfma_f32_16x16x32_bf16 v[40:43], v[154:157], v[170:173], v[40:43]
	v_mfma_f32_16x16x32_bf16 v[32:35], v[146:149], v[178:181], v[32:35]
	v_mfma_f32_16x16x32_bf16 v[24:27], v[154:157], v[178:181], v[24:27]
	v_mfma_f32_16x16x32_bf16 v[16:19], v[146:149], v[186:189], v[16:19]
	v_mfma_f32_16x16x32_bf16 v[8:11], v[154:157], v[186:189], v[8:11]
	v_mfma_f32_16x16x32_bf16 v[60:63], v[150:153], v[166:169], v[60:63]
	v_mfma_f32_16x16x32_bf16 v[56:59], v[158:161], v[166:169], v[56:59]
	v_mfma_f32_16x16x32_bf16 v[48:51], v[150:153], v[174:177], v[48:51]
	v_mfma_f32_16x16x32_bf16 v[40:43], v[158:161], v[174:177], v[40:43]
	v_mfma_f32_16x16x32_bf16 v[32:35], v[150:153], v[182:185], v[32:35]
	v_mfma_f32_16x16x32_bf16 v[24:27], v[158:161], v[182:185], v[24:27]
	v_mfma_f32_16x16x32_bf16 v[16:19], v[150:153], v[190:193], v[16:19]
	v_mfma_f32_16x16x32_bf16 v[8:11], v[158:161], v[190:193], v[8:11]
	s_barrier
	s_add_u32 s52, s52, 0x40080
	s_addc_u32 s53, s53, 0
	s_add_i32 s64, s64, s60
	v_lshl_add_u64 v[146:147], s[52:53], 0, v[128:129]
	s_mov_b32 m0, s64
	s_nop 0
	global_load_lds_dwordx4 v[146:147], off
	v_lshl_add_u64 v[146:147], s[52:53], 0, v[130:131]
	s_add_i32 m0, s64, 0x2000
	s_nop 0
	global_load_lds_dwordx4 v[146:147], off
	s_waitcnt vmcnt(6)
	s_barrier
	v_mfma_f32_16x16x32_bf16 v[52:55], v[198:201], v[162:165], v[52:55]
	v_mfma_f32_16x16x32_bf16 v[44:47], v[206:209], v[162:165], v[44:47]
	v_mfma_f32_16x16x32_bf16 v[36:39], v[198:201], v[170:173], v[36:39]
	v_mfma_f32_16x16x32_bf16 v[28:31], v[206:209], v[170:173], v[28:31]
	v_mfma_f32_16x16x32_bf16 v[20:23], v[198:201], v[178:181], v[20:23]
	v_mfma_f32_16x16x32_bf16 v[12:15], v[206:209], v[178:181], v[12:15]
	v_mfma_f32_16x16x32_bf16 v[4:7], v[198:201], v[186:189], v[4:7]
	v_mfma_f32_16x16x32_bf16 v[0:3], v[206:209], v[186:189], v[0:3]
	v_mfma_f32_16x16x32_bf16 v[52:55], v[202:205], v[166:169], v[52:55]
	v_mfma_f32_16x16x32_bf16 v[44:47], v[210:213], v[166:169], v[44:47]
	v_mfma_f32_16x16x32_bf16 v[36:39], v[202:205], v[174:177], v[36:39]
	v_mfma_f32_16x16x32_bf16 v[28:31], v[210:213], v[174:177], v[28:31]
	v_mfma_f32_16x16x32_bf16 v[20:23], v[202:205], v[182:185], v[20:23]
	v_mfma_f32_16x16x32_bf16 v[12:15], v[210:213], v[182:185], v[12:15]
	v_mfma_f32_16x16x32_bf16 v[4:7], v[202:205], v[190:193], v[4:7]
	v_mfma_f32_16x16x32_bf16 v[0:3], v[210:213], v[190:193], v[0:3]
	s_add_i32 s79, s79, 2
	s_add_u32 s50, s50, 0x100
	s_addc_u32 s51, s51, 0
	s_cmp_gt_u32 s79, 13
	s_barrier
	s_cbranch_scc0 .LBB0_528
	s_add_u32 s50, s75, 0xffffff00
	s_addc_u32 s51, s76, -1
	s_andn2_b64 vcc, exec, s[6:7]
	s_cbranch_vccnz .LBB0_531
	v_mov_b32_e32 v0, 0
	s_mov_b32 s9, s24
	s_mov_b32 s8, s44
	s_mov_b64 s[20:21], s[48:49]
	s_mov_b32 s71, s74
	v_mov_b32_e32 v1, v0
	v_mov_b32_e32 v2, v0
	v_mov_b32_e32 v3, v0
	v_mov_b32_e32 v4, v0
	v_mov_b32_e32 v5, v0
	v_mov_b32_e32 v6, v0
	v_mov_b32_e32 v7, v0
	v_mov_b32_e32 v12, v0
	v_mov_b32_e32 v13, v0
	v_mov_b32_e32 v14, v0
	v_mov_b32_e32 v15, v0
	v_mov_b32_e32 v20, v0
	v_mov_b32_e32 v21, v0
	v_mov_b32_e32 v22, v0
	v_mov_b32_e32 v23, v0
	v_mov_b32_e32 v28, v0
	v_mov_b32_e32 v29, v0
	v_mov_b32_e32 v30, v0
	v_mov_b32_e32 v31, v0
	v_mov_b32_e32 v36, v0
	v_mov_b32_e32 v37, v0
	v_mov_b32_e32 v38, v0
	v_mov_b32_e32 v39, v0
	v_mov_b32_e32 v44, v0
	v_mov_b32_e32 v45, v0
	v_mov_b32_e32 v46, v0
	v_mov_b32_e32 v47, v0
	v_mov_b32_e32 v52, v0
	v_mov_b32_e32 v53, v0
	v_mov_b32_e32 v54, v0
	v_mov_b32_e32 v55, v0
	v_mov_b32_e32 v8, v0
	v_mov_b32_e32 v9, v0
	v_mov_b32_e32 v10, v0
	v_mov_b32_e32 v11, v0
	v_mov_b32_e32 v16, v0
	v_mov_b32_e32 v17, v0
	v_mov_b32_e32 v18, v0
	v_mov_b32_e32 v19, v0
	v_mov_b32_e32 v24, v0
	v_mov_b32_e32 v25, v0
	v_mov_b32_e32 v26, v0
	v_mov_b32_e32 v27, v0
	v_mov_b32_e32 v32, v0
	v_mov_b32_e32 v33, v0
	v_mov_b32_e32 v34, v0
	v_mov_b32_e32 v35, v0
	v_mov_b32_e32 v40, v0
	v_mov_b32_e32 v41, v0
	v_mov_b32_e32 v42, v0
	v_mov_b32_e32 v43, v0
	v_mov_b32_e32 v48, v0
	v_mov_b32_e32 v49, v0
	v_mov_b32_e32 v50, v0
	v_mov_b32_e32 v51, v0
	v_mov_b32_e32 v56, v0
	v_mov_b32_e32 v57, v0
	v_mov_b32_e32 v58, v0
	v_mov_b32_e32 v59, v0
	v_mov_b32_e32 v60, v0
	v_mov_b32_e32 v61, v0
	v_mov_b32_e32 v62, v0
	v_mov_b32_e32 v63, v0
	v_mov_b32_e32 v64, v0
	v_mov_b32_e32 v65, v0
	v_mov_b32_e32 v66, v0
	v_mov_b32_e32 v67, v0
	v_mov_b32_e32 v68, v0
	v_mov_b32_e32 v69, v0
	v_mov_b32_e32 v70, v0
	v_mov_b32_e32 v71, v0
	v_mov_b32_e32 v76, v0
	v_mov_b32_e32 v77, v0
	v_mov_b32_e32 v78, v0
	v_mov_b32_e32 v79, v0
	v_mov_b32_e32 v84, v0
	v_mov_b32_e32 v85, v0
	v_mov_b32_e32 v86, v0
	v_mov_b32_e32 v87, v0
	v_mov_b32_e32 v92, v0
	v_mov_b32_e32 v93, v0
	v_mov_b32_e32 v94, v0
	v_mov_b32_e32 v95, v0
	v_mov_b32_e32 v100, v0
	v_mov_b32_e32 v101, v0
	v_mov_b32_e32 v102, v0
	v_mov_b32_e32 v103, v0
	v_mov_b32_e32 v108, v0
	v_mov_b32_e32 v109, v0
	v_mov_b32_e32 v110, v0
	v_mov_b32_e32 v111, v0
	v_mov_b32_e32 v116, v0
	v_mov_b32_e32 v117, v0
	v_mov_b32_e32 v118, v0
	v_mov_b32_e32 v119, v0
	v_mov_b32_e32 v72, v0
	v_mov_b32_e32 v73, v0
	v_mov_b32_e32 v74, v0
	v_mov_b32_e32 v75, v0
	v_mov_b32_e32 v80, v0
	v_mov_b32_e32 v81, v0
	v_mov_b32_e32 v82, v0
	v_mov_b32_e32 v83, v0
	v_mov_b32_e32 v88, v0
	v_mov_b32_e32 v89, v0
	v_mov_b32_e32 v90, v0
	v_mov_b32_e32 v91, v0
	v_mov_b32_e32 v96, v0
	v_mov_b32_e32 v97, v0
	v_mov_b32_e32 v98, v0
	v_mov_b32_e32 v99, v0
	v_mov_b32_e32 v104, v0
	v_mov_b32_e32 v105, v0
	v_mov_b32_e32 v106, v0
	v_mov_b32_e32 v107, v0
	v_mov_b32_e32 v112, v0
	v_mov_b32_e32 v113, v0
	v_mov_b32_e32 v114, v0
	v_mov_b32_e32 v115, v0
	v_mov_b32_e32 v120, v0
	v_mov_b32_e32 v121, v0
	v_mov_b32_e32 v122, v0
	v_mov_b32_e32 v123, v0
	v_mov_b32_e32 v124, v0
	v_mov_b32_e32 v125, v0
	v_mov_b32_e32 v126, v0
	v_mov_b32_e32 v127, v0
	s_andn2_b64 vcc, exec, s[4:5]
	s_cbranch_vccnz .LBB0_532
	s_branch .LBB0_533

; #define PG8_STAGE(bufoff, gbase, voff) do { _Pragma("unroll") for (int _i = 0; _i < 2; ++_i) \
;         __builtin_amdgcn_global_load_lds((const unsigned*)((const char*)(gbase) + (voff)[_i]), (LAS unsigned*)(lds + (bufoff) + ldsw + _i * 8192), 16, 0, 0); } while (0)
; #define PG8_LDA(dst, b, h) do { _Pragma("unroll") for (int m = 0; m < 4; ++m) _Pragma("unroll") for (int k = 0; k < 2; ++k) dst[m][k] = *(const LAS bf16x8*)(lds + PG8_SA(b, h) + aoff + m * 2048 + k * 1024); } while (0)
; #define PG8_LDB(dst, b, h) do { _Pragma("unroll") for (int n = 0; n < 2; ++n) _Pragma("unroll") for (int k = 0; k < 2; ++k) dst[n][k] = *(const LAS bf16x8*)(lds + PG8_SB(b, h) + boff + n * 2048 + k * 1024); } while (0)
; #define PG8_MMA(ai, bj, At, Bt) do { __builtin_amdgcn_s_setprio(1); _Pragma("unroll") for (int m = 0; m < 4; ++m) _Pragma("unroll") for (int n = 0; n < 2; ++n) _Pragma("unroll") for (int k = 0; k < 2; ++k) \
;         acc[ai][bj][m][n] = __builtin_amdgcn_mfma_f32_16x16x32_bf16(Bt[n][k], At[m][k], acc[ai][bj][m][n], 0, 0, 0); __builtin_amdgcn_s_setprio(0); } while (0)
; #define PG8_WAIT_V(n) asm volatile("s_waitcnt vmcnt(" #n ")" ::: "memory")
; #define PG8_WAIT_L(n) asm volatile("s_waitcnt lgkmcnt(" #n ")" ::: "memory")
; #define PG8_BAR __builtin_amdgcn_s_barrier()
; #define PG8_SCHED __builtin_amdgcn_sched_barrier(0)
; template <class Epi>
; __device__ __forceinline__ void gemm_phase(LAS unsigned char* lds, const Gemm g, const StaticOrder& S, const Epi& E, float* smem = nullptr) {
;     ...
;             PG8_LDB(B0, 0, 0); PG8_SCHED; PG8_LDA(At, 0, 0); PG8_STAGE(PG8_SA(1, 1), a1 + hstep, voffA);
;             PG8_WAIT_L(8); PG8_BAR; PG8_WAIT_L(0); PG8_MMA(0, 0, At, B0); PG8_BAR; PG8_SCHED;
;             PG8_LDB(B1, 0, 1); PG8_STAGE(PG8_SB(0, 0), b2, voffA);
;             PG8_BAR; PG8_WAIT_L(0); PG8_MMA(0, 1, At, B1); PG8_BAR;
;             PG8_LDA(At, 0, 1); PG8_STAGE(PG8_SA(0, 0), a2, voffA);
;             PG8_BAR; PG8_WAIT_L(0); PG8_MMA(1, 0, At, B0); PG8_BAR; PG8_SCHED;
;             PG8_STAGE(PG8_SB(0, 1), b2 + hstep, voffA);
;             PG8_WAIT_V(6); PG8_BAR; PG8_MMA(1, 1, At, B1); PG8_BAR;
.LBB0_668:
	ds_read_b128 v[150:153], v146
	ds_read_b128 v[154:157], v146 offset:1024
	ds_read_b128 v[158:161], v146 offset:2048
	ds_read_b128 v[162:165], v146 offset:3072
	s_add_u32 s64, s62, 0xfffc0080
	s_addc_u32 s65, s63, -1
	s_cmp_eq_u32 s85, 12
	s_cselect_b32 s67, s47, s65
	s_cselect_b32 s66, s81, s64
	s_cselect_b32 s65, s45, s84
	s_cselect_b32 s64, s82, s83
	v_lshl_add_u64 v[142:143], s[62:63], 0, v[134:135]
	s_add_i32 m0, s60, 0xc000
	ds_read_b128 v[166:169], v147
	ds_read_b128 v[170:173], v147 offset:1024
	ds_read_b128 v[174:177], v147 offset:2048
	ds_read_b128 v[178:181], v147 offset:3072
	ds_read_b128 v[182:185], v147 offset:4096
	ds_read_b128 v[186:189], v147 offset:5120
	ds_read_b128 v[190:193], v147 offset:6144
	ds_read_b128 v[194:197], v147 offset:7168
	global_load_lds_dwordx4 v[142:143], off
	v_lshl_add_u64 v[142:143], s[62:63], 0, v[136:137]
	s_add_i32 m0, s60, 0xe000
	s_nop 0
	global_load_lds_dwordx4 v[142:143], off
	s_waitcnt lgkmcnt(8)
	s_barrier
	s_waitcnt lgkmcnt(0)
	s_waitcnt lgkmcnt(0)
	v_mfma_f32_16x16x32_bf16 v[124:127], v[150:153], v[166:169], v[124:127]
	v_mfma_f32_16x16x32_bf16 v[120:123], v[158:161], v[166:169], v[120:123]
	v_mfma_f32_16x16x32_bf16 v[108:111], v[150:153], v[174:177], v[108:111]
	v_mfma_f32_16x16x32_bf16 v[104:107], v[158:161], v[174:177], v[104:107]
	v_mfma_f32_16x16x32_bf16 v[92:95], v[150:153], v[182:185], v[92:95]
	v_mfma_f32_16x16x32_bf16 v[88:91], v[158:161], v[182:185], v[88:91]
	v_mfma_f32_16x16x32_bf16 v[76:79], v[150:153], v[190:193], v[76:79]
	v_mfma_f32_16x16x32_bf16 v[72:75], v[158:161], v[190:193], v[72:75]
	v_mfma_f32_16x16x32_bf16 v[124:127], v[154:157], v[170:173], v[124:127]
	v_mfma_f32_16x16x32_bf16 v[120:123], v[162:165], v[170:173], v[120:123]
	v_mfma_f32_16x16x32_bf16 v[108:111], v[154:157], v[178:181], v[108:111]
	v_mfma_f32_16x16x32_bf16 v[104:107], v[162:165], v[178:181], v[104:107]
	v_mfma_f32_16x16x32_bf16 v[92:95], v[154:157], v[186:189], v[92:95]
	v_mfma_f32_16x16x32_bf16 v[88:91], v[162:165], v[186:189], v[88:91]
	v_mfma_f32_16x16x32_bf16 v[76:79], v[154:157], v[194:197], v[76:79]
	v_mfma_f32_16x16x32_bf16 v[72:75], v[162:165], v[194:197], v[72:75]
	s_barrier
	s_add_i32 s86, s74, s33
	v_lshl_add_u64 v[142:143], s[64:65], 0, v[128:129]
	s_mov_b32 m0, s86
	ds_read_b128 v[198:201], v148
	ds_read_b128 v[202:205], v148 offset:1024
	ds_read_b128 v[206:209], v148 offset:2048
	ds_read_b128 v[210:213], v148 offset:3072
	global_load_lds_dwordx4 v[142:143], off
	v_lshl_add_u64 v[214:215], s[64:65], 0, v[130:131]
	s_add_i32 m0, s86, 0x2000
	s_nop 0
	global_load_lds_dwordx4 v[214:215], off
	s_barrier
	s_waitcnt lgkmcnt(0)
	s_waitcnt lgkmcnt(0)
	v_mfma_f32_16x16x32_bf16 v[116:119], v[198:201], v[166:169], v[116:119]
	v_mfma_f32_16x16x32_bf16 v[112:115], v[206:209], v[166:169], v[112:115]
	v_mfma_f32_16x16x32_bf16 v[100:103], v[198:201], v[174:177], v[100:103]
	v_mfma_f32_16x16x32_bf16 v[96:99], v[206:209], v[174:177], v[96:99]
	v_mfma_f32_16x16x32_bf16 v[84:87], v[198:201], v[182:185], v[84:87]
	v_mfma_f32_16x16x32_bf16 v[80:83], v[206:209], v[182:185], v[80:83]
	v_mfma_f32_16x16x32_bf16 v[68:71], v[198:201], v[190:193], v[68:71]
	v_mfma_f32_16x16x32_bf16 v[64:67], v[206:209], v[190:193], v[64:67]
	v_mfma_f32_16x16x32_bf16 v[116:119], v[202:205], v[170:173], v[116:119]
	v_mfma_f32_16x16x32_bf16 v[112:115], v[210:213], v[170:173], v[112:115]
	v_mfma_f32_16x16x32_bf16 v[100:103], v[202:205], v[178:181], v[100:103]
	v_mfma_f32_16x16x32_bf16 v[96:99], v[210:213], v[178:181], v[96:99]
	v_mfma_f32_16x16x32_bf16 v[84:87], v[202:205], v[186:189], v[84:87]
	v_mfma_f32_16x16x32_bf16 v[80:83], v[210:213], v[186:189], v[80:83]
	v_mfma_f32_16x16x32_bf16 v[68:71], v[202:205], v[194:197], v[68:71]
	v_mfma_f32_16x16x32_bf16 v[64:67], v[210:213], v[194:197], v[64:67]
	s_mov_b32 m0, s60
	v_lshl_add_u64 v[216:217], s[66:67], 0, v[128:129]
	s_barrier
	ds_read_b128 v[166:169], v147 offset:16384
	ds_read_b128 v[170:173], v147 offset:17408
	ds_read_b128 v[174:177], v147 offset:18432
	ds_read_b128 v[178:181], v147 offset:19456
	ds_read_b128 v[182:185], v147 offset:20480
	ds_read_b128 v[186:189], v147 offset:21504
	ds_read_b128 v[190:193], v147 offset:22528
	ds_read_b128 v[194:197], v147 offset:23552
	global_load_lds_dwordx4 v[216:217], off
	v_lshl_add_u64 v[218:219], s[66:67], 0, v[130:131]
	s_mov_b32 m0, s61
	s_nop 0
	global_load_lds_dwordx4 v[218:219], off
	s_barrier
	s_waitcnt lgkmcnt(0)
	s_waitcnt lgkmcnt(0)
	v_mfma_f32_16x16x32_bf16 v[60:63], v[150:153], v[166:169], v[60:63]
	v_mfma_f32_16x16x32_bf16 v[56:59], v[158:161], v[166:169], v[56:59]
	v_mfma_f32_16x16x32_bf16 v[44:47], v[150:153], v[174:177], v[44:47]
	v_mfma_f32_16x16x32_bf16 v[40:43], v[158:161], v[174:177], v[40:43]
	v_mfma_f32_16x16x32_bf16 v[28:31], v[150:153], v[182:185], v[28:31]
	v_mfma_f32_16x16x32_bf16 v[24:27], v[158:161], v[182:185], v[24:27]
	v_mfma_f32_16x16x32_bf16 v[12:15], v[150:153], v[190:193], v[12:15]
	v_mfma_f32_16x16x32_bf16 v[8:11], v[158:161], v[190:193], v[8:11]
	v_mfma_f32_16x16x32_bf16 v[60:63], v[154:157], v[170:173], v[60:63]
	v_mfma_f32_16x16x32_bf16 v[56:59], v[162:165], v[170:173], v[56:59]
	v_mfma_f32_16x16x32_bf16 v[44:47], v[154:157], v[178:181], v[44:47]
	v_mfma_f32_16x16x32_bf16 v[40:43], v[162:165], v[178:181], v[40:43]
	v_mfma_f32_16x16x32_bf16 v[28:31], v[154:157], v[186:189], v[28:31]
	v_mfma_f32_16x16x32_bf16 v[24:27], v[162:165], v[186:189], v[24:27]
	v_mfma_f32_16x16x32_bf16 v[12:15], v[154:157], v[194:197], v[12:15]
	v_mfma_f32_16x16x32_bf16 v[8:11], v[162:165], v[194:197], v[8:11]
	s_barrier
; #define PG8_STAGE(bufoff, gbase, voff) do { _Pragma("unroll") for (int _i = 0; _i < 2; ++_i) \
;         __builtin_amdgcn_global_load_lds((const unsigned*)((const char*)(gbase) + (voff)[_i]), (LAS unsigned*)(lds + (bufoff) + ldsw + _i * 8192), 16, 0, 0); } while (0)
; #define PG8_LDA(dst, b, h) do { _Pragma("unroll") for (int m = 0; m < 4; ++m) _Pragma("unroll") for (int k = 0; k < 2; ++k) dst[m][k] = *(const LAS bf16x8*)(lds + PG8_SA(b, h) + aoff + m * 2048 + k * 1024); } while (0)
; #define PG8_LDB(dst, b, h) do { _Pragma("unroll") for (int n = 0; n < 2; ++n) _Pragma("unroll") for (int k = 0; k < 2; ++k) dst[n][k] = *(const LAS bf16x8*)(lds + PG8_SB(b, h) + boff + n * 2048 + k * 1024); } while (0)
; #define PG8_MMA(ai, bj, At, Bt) do { __builtin_amdgcn_s_setprio(1); _Pragma("unroll") for (int m = 0; m < 4; ++m) _Pragma("unroll") for (int n = 0; n < 2; ++n) _Pragma("unroll") for (int k = 0; k < 2; ++k) \
;         acc[ai][bj][m][n] = __builtin_amdgcn_mfma_f32_16x16x32_bf16(Bt[n][k], At[m][k], acc[ai][bj][m][n], 0, 0, 0); __builtin_amdgcn_s_setprio(0); } while (0)
; #define PG8_WAIT_V(n) asm volatile("s_waitcnt vmcnt(" #n ")" ::: "memory")
; #define PG8_WAIT_L(n) asm volatile("s_waitcnt lgkmcnt(" #n ")" ::: "memory")
; #define PG8_BAR __builtin_amdgcn_s_barrier()
; #define PG8_SCHED __builtin_amdgcn_sched_barrier(0)
; template <class Epi>
; __device__ __forceinline__ void gemm_phase(LAS unsigned char* lds, const Gemm g, const StaticOrder& S, const Epi& E, float* smem = nullptr) {
;     ...
;             PG8_WAIT_V(6); PG8_BAR; PG8_MMA(1, 1, At, B1); PG8_BAR;
;             PG8_LDB(B0, 1, 0); PG8_SCHED; PG8_LDA(At, 1, 0); PG8_STAGE(PG8_SA(0, 1), a2 + hstep, voffA);
;             PG8_WAIT_L(8); PG8_BAR; PG8_WAIT_L(0); PG8_MMA(0, 0, At, B0); PG8_BAR; PG8_SCHED;
;             PG8_LDB(B1, 1, 1); PG8_STAGE(PG8_SB(1, 0), b3, voffA);
;             PG8_BAR; PG8_WAIT_L(0); PG8_MMA(0, 1, At, B1); PG8_BAR;
;             PG8_LDA(At, 1, 1); PG8_STAGE(PG8_SA(1, 0), a3, voffA);
	s_add_u32 s86, s64, 0x40000
	s_addc_u32 s87, s65, 0
	s_add_i32 s88, s75, s33
	v_lshl_add_u64 v[150:151], s[86:87], 0, v[128:129]
	s_mov_b32 m0, s88
	s_nop 0
	global_load_lds_dwordx4 v[150:151], off
	v_lshl_add_u64 v[150:151], s[86:87], 0, v[130:131]
	s_add_i32 m0, s88, 0x2000
	s_nop 0
	global_load_lds_dwordx4 v[150:151], off
	s_waitcnt vmcnt(6)
	s_barrier
	v_mfma_f32_16x16x32_bf16 v[52:55], v[198:201], v[166:169], v[52:55]
	v_mfma_f32_16x16x32_bf16 v[48:51], v[206:209], v[166:169], v[48:51]
	v_mfma_f32_16x16x32_bf16 v[36:39], v[198:201], v[174:177], v[36:39]
	v_mfma_f32_16x16x32_bf16 v[32:35], v[206:209], v[174:177], v[32:35]
	v_mfma_f32_16x16x32_bf16 v[20:23], v[198:201], v[182:185], v[20:23]
	v_mfma_f32_16x16x32_bf16 v[16:19], v[206:209], v[182:185], v[16:19]
	v_mfma_f32_16x16x32_bf16 v[4:7], v[198:201], v[190:193], v[4:7]
	v_mfma_f32_16x16x32_bf16 v[0:3], v[206:209], v[190:193], v[0:3]
	v_mfma_f32_16x16x32_bf16 v[52:55], v[202:205], v[170:173], v[52:55]
	v_mfma_f32_16x16x32_bf16 v[48:51], v[210:213], v[170:173], v[48:51]
	v_mfma_f32_16x16x32_bf16 v[36:39], v[202:205], v[178:181], v[36:39]
	v_mfma_f32_16x16x32_bf16 v[32:35], v[210:213], v[178:181], v[32:35]
	v_mfma_f32_16x16x32_bf16 v[20:23], v[202:205], v[186:189], v[20:23]
	v_mfma_f32_16x16x32_bf16 v[16:19], v[210:213], v[186:189], v[16:19]
	v_mfma_f32_16x16x32_bf16 v[4:7], v[202:205], v[194:197], v[4:7]
	v_mfma_f32_16x16x32_bf16 v[0:3], v[210:213], v[194:197], v[0:3]
	s_add_i32 s86, 16, 0x18000
	v_add_u32_e32 v149, s86, v145
	s_barrier
	ds_read_b128 v[150:153], v149
	ds_read_b128 v[154:157], v149 offset:1024
	ds_read_b128 v[158:161], v149 offset:2048
	ds_read_b128 v[162:165], v149 offset:3072
	s_add_u32 s66, s66, 0x40000
	s_addc_u32 s67, s67, 0
	s_mov_b32 m0, s68
	v_lshl_add_u64 v[198:199], s[66:67], 0, v[128:129]
	ds_read_b128 v[166:169], v147 offset:32768
	ds_read_b128 v[170:173], v147 offset:33792
	ds_read_b128 v[174:177], v147 offset:34816
	ds_read_b128 v[178:181], v147 offset:35840
	ds_read_b128 v[182:185], v147 offset:36864
	ds_read_b128 v[186:189], v147 offset:37888
	ds_read_b128 v[190:193], v147 offset:38912
	ds_read_b128 v[194:197], v147 offset:39936
	global_load_lds_dwordx4 v[198:199], off
	v_lshl_add_u64 v[198:199], s[66:67], 0, v[130:131]
	s_mov_b32 m0, s69
	s_nop 0
	global_load_lds_dwordx4 v[198:199], off
	s_waitcnt lgkmcnt(8)
	s_barrier
	s_waitcnt lgkmcnt(0)
	s_waitcnt lgkmcnt(0)
	v_mfma_f32_16x16x32_bf16 v[124:127], v[150:153], v[166:169], v[124:127]
	v_mfma_f32_16x16x32_bf16 v[120:123], v[158:161], v[166:169], v[120:123]
	v_mfma_f32_16x16x32_bf16 v[108:111], v[150:153], v[174:177], v[108:111]
	v_mfma_f32_16x16x32_bf16 v[104:107], v[158:161], v[174:177], v[104:107]
	v_mfma_f32_16x16x32_bf16 v[92:95], v[150:153], v[182:185], v[92:95]
	v_mfma_f32_16x16x32_bf16 v[88:91], v[158:161], v[182:185], v[88:91]
	v_mfma_f32_16x16x32_bf16 v[76:79], v[150:153], v[190:193], v[76:79]
	v_mfma_f32_16x16x32_bf16 v[72:75], v[158:161], v[190:193], v[72:75]
	v_mfma_f32_16x16x32_bf16 v[124:127], v[154:157], v[170:173], v[124:127]
	v_mfma_f32_16x16x32_bf16 v[120:123], v[162:165], v[170:173], v[120:123]
	v_mfma_f32_16x16x32_bf16 v[108:111], v[154:157], v[178:181], v[108:111]
	v_mfma_f32_16x16x32_bf16 v[104:107], v[162:165], v[178:181], v[104:107]
	v_mfma_f32_16x16x32_bf16 v[92:95], v[154:157], v[186:189], v[92:95]
	v_mfma_f32_16x16x32_bf16 v[88:91], v[162:165], v[186:189], v[88:91]
	v_mfma_f32_16x16x32_bf16 v[76:79], v[154:157], v[194:197], v[76:79]
	v_mfma_f32_16x16x32_bf16 v[72:75], v[162:165], v[194:197], v[72:75]
	s_barrier
	s_add_i32 s66, 16, 0x1c000
	s_add_i32 s67, s86, s33
	v_add_u32_e32 v149, s66, v145
	v_lshl_add_u64 v[142:143], v[142:143], 0, s[0:1]
	s_mov_b32 m0, s67
	ds_read_b128 v[198:201], v149
	ds_read_b128 v[202:205], v149 offset:1024
	ds_read_b128 v[206:209], v149 offset:2048
	ds_read_b128 v[210:213], v149 offset:3072
	global_load_lds_dwordx4 v[142:143], off
	v_lshl_add_u64 v[142:143], v[214:215], 0, s[0:1]
	s_add_i32 m0, s67, 0x2000
	s_nop 0
	global_load_lds_dwordx4 v[142:143], off
	s_barrier
	s_waitcnt lgkmcnt(0)
	s_waitcnt lgkmcnt(0)
	v_mfma_f32_16x16x32_bf16 v[116:119], v[198:201], v[166:169], v[116:119]
	v_mfma_f32_16x16x32_bf16 v[112:115], v[206:209], v[166:169], v[112:115]
	v_mfma_f32_16x16x32_bf16 v[100:103], v[198:201], v[174:177], v[100:103]
	v_mfma_f32_16x16x32_bf16 v[96:99], v[206:209], v[174:177], v[96:99]
	v_mfma_f32_16x16x32_bf16 v[84:87], v[198:201], v[182:185], v[84:87]
	v_mfma_f32_16x16x32_bf16 v[80:83], v[206:209], v[182:185], v[80:83]
	v_mfma_f32_16x16x32_bf16 v[68:71], v[198:201], v[190:193], v[68:71]
	v_mfma_f32_16x16x32_bf16 v[64:67], v[206:209], v[190:193], v[64:67]
	v_mfma_f32_16x16x32_bf16 v[116:119], v[202:205], v[170:173], v[116:119]
	v_mfma_f32_16x16x32_bf16 v[112:115], v[210:213], v[170:173], v[112:115]
	v_mfma_f32_16x16x32_bf16 v[100:103], v[202:205], v[178:181], v[100:103]
	v_mfma_f32_16x16x32_bf16 v[96:99], v[210:213], v[178:181], v[96:99]
	v_mfma_f32_16x16x32_bf16 v[84:87], v[202:205], v[186:189], v[84:87]
	v_mfma_f32_16x16x32_bf16 v[80:83], v[210:213], v[186:189], v[80:83]
	v_mfma_f32_16x16x32_bf16 v[68:71], v[202:205], v[194:197], v[68:71]
	v_mfma_f32_16x16x32_bf16 v[64:67], v[210:213], v[194:197], v[64:67]
	s_mov_b32 m0, s70
	v_lshl_add_u64 v[142:143], v[216:217], 0, s[0:1]
	s_barrier
	ds_read_b128 v[166:169], v147 offset:49152
	ds_read_b128 v[170:173], v147 offset:50176
	ds_read_b128 v[174:177], v147 offset:51200
	ds_read_b128 v[178:181], v147 offset:52224
	ds_read_b128 v[182:185], v147 offset:53248
	ds_read_b128 v[186:189], v147 offset:54272
	ds_read_b128 v[190:193], v147 offset:55296
	ds_read_b128 v[194:197], v147 offset:56320
	global_load_lds_dwordx4 v[142:143], off
	v_lshl_add_u64 v[142:143], v[218:219], 0, s[0:1]
	s_mov_b32 m0, s71
	s_nop 0
	global_load_lds_dwordx4 v[142:143], off
	s_barrier
; __device__ __forceinline__ void st_bf16x8(bf16_t* p, const f32x4 a, const f32x4 b) { uint4 o; o.x = cvt_pk_bf16(a[0], a[1]); o.y = cvt_pk_bf16(a[2], a[3]); o.z = cvt_pk_bf16(b[0], b[1]); o.w = cvt_pk_bf16(b[2], b[3]); *(uint4*)p = o; }
; #define PG8_STAGE(bufoff, gbase, voff) do { _Pragma("unroll") for (int _i = 0; _i < 2; ++_i) \
;         __builtin_amdgcn_global_load_lds((const unsigned*)((const char*)(gbase) + (voff)[_i]), (LAS unsigned*)(lds + (bufoff) + ldsw + _i * 8192), 16, 0, 0); } while (0)
; #define PG8_LDA(dst, b, h) do { _Pragma("unroll") for (int m = 0; m < 4; ++m) _Pragma("unroll") for (int k = 0; k < 2; ++k) dst[m][k] = *(const LAS bf16x8*)(lds + PG8_SA(b, h) + aoff + m * 2048 + k * 1024); } while (0)
; #define PG8_MMA(ai, bj, At, Bt) do { __builtin_amdgcn_s_setprio(1); _Pragma("unroll") for (int m = 0; m < 4; ++m) _Pragma("unroll") for (int n = 0; n < 2; ++n) _Pragma("unroll") for (int k = 0; k < 2; ++k) \
;         acc[ai][bj][m][n] = __builtin_amdgcn_mfma_f32_16x16x32_bf16(Bt[n][k], At[m][k], acc[ai][bj][m][n], 0, 0, 0); __builtin_amdgcn_s_setprio(0); } while (0)
; #define PG8_WAIT_V(n) asm volatile("s_waitcnt vmcnt(" #n ")" ::: "memory")
; #define PG8_WAIT_L(n) asm volatile("s_waitcnt lgkmcnt(" #n ")" ::: "memory")
; #define PG8_BAR __builtin_amdgcn_s_barrier()
; #define PG8_SCHED __builtin_amdgcn_sched_barrier(0)
;     __device__ __forceinline__ void row(const f32x4 (&a)[2][2], int row, int pn, int wc, int fq) const {
;         bf16_t* rp = T + (size_t)row * DFF + pn * BM + wc * 32 + 8 * fq;
; #pragma unroll
;         for (int bj = 0; bj < 2; ++bj) { f32x4 v0 = a[bj][0], v1 = a[bj][1];
; #pragma unroll
;             for (int j = 0; j < 4; ++j) { const float r0 = fmaxf(v0[j], 0.f), r1 = fmaxf(v1[j], 0.f); v0[j] = r0 * r0; v1[j] = r1 * r1; }
;             st_bf16x8(rp + bj * HALF, v0, v1); }
; template <class Epi>
; __device__ __forceinline__ void gemm_phase(LAS unsigned char* lds, const Gemm g, const StaticOrder& S, const Epi& E, float* smem = nullptr) {
;     ...
;             PG8_LDA(At, 1, 1); PG8_STAGE(PG8_SA(1, 0), a3, voffA);
;             PG8_BAR; PG8_WAIT_L(0); PG8_MMA(1, 0, At, B0); PG8_BAR; PG8_SCHED;
;             PG8_STAGE(PG8_SB(1, 1), b3 + hstep, voffA);
;             PG8_WAIT_V(6); PG8_BAR; PG8_MMA(1, 1, At, B1); PG8_BAR;
	s_waitcnt lgkmcnt(0)
	s_waitcnt lgkmcnt(0)
	v_mfma_f32_16x16x32_bf16 v[60:63], v[150:153], v[166:169], v[60:63]
	v_mfma_f32_16x16x32_bf16 v[56:59], v[158:161], v[166:169], v[56:59]
	v_mfma_f32_16x16x32_bf16 v[44:47], v[150:153], v[174:177], v[44:47]
	v_mfma_f32_16x16x32_bf16 v[40:43], v[158:161], v[174:177], v[40:43]
	v_mfma_f32_16x16x32_bf16 v[28:31], v[150:153], v[182:185], v[28:31]
	v_mfma_f32_16x16x32_bf16 v[24:27], v[158:161], v[182:185], v[24:27]
	v_mfma_f32_16x16x32_bf16 v[12:15], v[150:153], v[190:193], v[12:15]
	v_mfma_f32_16x16x32_bf16 v[8:11], v[158:161], v[190:193], v[8:11]
	v_mfma_f32_16x16x32_bf16 v[60:63], v[154:157], v[170:173], v[60:63]
	v_mfma_f32_16x16x32_bf16 v[56:59], v[162:165], v[170:173], v[56:59]
	v_mfma_f32_16x16x32_bf16 v[44:47], v[154:157], v[178:181], v[44:47]
	v_mfma_f32_16x16x32_bf16 v[40:43], v[162:165], v[178:181], v[40:43]
	v_mfma_f32_16x16x32_bf16 v[28:31], v[154:157], v[186:189], v[28:31]
	v_mfma_f32_16x16x32_bf16 v[24:27], v[162:165], v[186:189], v[24:27]
	v_mfma_f32_16x16x32_bf16 v[12:15], v[154:157], v[194:197], v[12:15]
	v_mfma_f32_16x16x32_bf16 v[8:11], v[162:165], v[194:197], v[8:11]
	s_barrier
	s_add_u32 s64, s64, 0x40080
	s_addc_u32 s65, s65, 0
	s_add_i32 s66, s66, s33
	v_lshl_add_u64 v[142:143], s[64:65], 0, v[128:129]
	s_mov_b32 m0, s66
	s_nop 0
	global_load_lds_dwordx4 v[142:143], off
	v_lshl_add_u64 v[142:143], s[64:65], 0, v[130:131]
	s_add_i32 m0, s66, 0x2000
	s_nop 0
	global_load_lds_dwordx4 v[142:143], off
	s_waitcnt vmcnt(6)
	s_barrier
	v_mfma_f32_16x16x32_bf16 v[52:55], v[198:201], v[166:169], v[52:55]
	v_mfma_f32_16x16x32_bf16 v[48:51], v[206:209], v[166:169], v[48:51]
	v_mfma_f32_16x16x32_bf16 v[36:39], v[198:201], v[174:177], v[36:39]
	v_mfma_f32_16x16x32_bf16 v[32:35], v[206:209], v[174:177], v[32:35]
	v_mfma_f32_16x16x32_bf16 v[20:23], v[198:201], v[182:185], v[20:23]
	v_mfma_f32_16x16x32_bf16 v[16:19], v[206:209], v[182:185], v[16:19]
	v_mfma_f32_16x16x32_bf16 v[4:7], v[198:201], v[190:193], v[4:7]
	v_mfma_f32_16x16x32_bf16 v[0:3], v[206:209], v[190:193], v[0:3]
	v_mfma_f32_16x16x32_bf16 v[52:55], v[202:205], v[170:173], v[52:55]
	v_mfma_f32_16x16x32_bf16 v[48:51], v[210:213], v[170:173], v[48:51]
	v_mfma_f32_16x16x32_bf16 v[36:39], v[202:205], v[178:181], v[36:39]
	v_mfma_f32_16x16x32_bf16 v[32:35], v[210:213], v[178:181], v[32:35]
	v_mfma_f32_16x16x32_bf16 v[20:23], v[202:205], v[186:189], v[20:23]
	v_mfma_f32_16x16x32_bf16 v[16:19], v[210:213], v[186:189], v[16:19]
	v_mfma_f32_16x16x32_bf16 v[4:7], v[202:205], v[194:197], v[4:7]
	v_mfma_f32_16x16x32_bf16 v[0:3], v[210:213], v[194:197], v[0:3]
	s_add_i32 s85, s85, 2
	s_add_u32 s62, s62, 0x100
	s_addc_u32 s63, s63, 0
	s_add_u32 s83, s83, 0x100
	s_addc_u32 s84, s84, 0
	s_cmp_gt_u32 s85, 13
	s_barrier
	s_cbranch_scc0 .LBB0_668
	v_lshl_add_u32 v150, s52, 8, v144
	s_lshl_b32 s52, s53, 8
	v_ashrrev_i32_e32 v151, 31, v150
	v_max_f32_e32 v120, v120, v120
	s_ashr_i32 s53, s52, 31
	v_lshlrev_b64 v[142:143], 13, v[150:151]
	v_max_f32_e32 v120, 0, v120
	v_max_f32_e32 v121, v121, v121
	v_max_f32_e32 v122, v122, v122
	v_lshl_add_u64 v[142:143], s[30:31], 0, v[142:143]
	s_lshl_b64 s[52:53], s[52:53], 1
	v_mul_f32_e32 v149, v120, v120
	v_max_f32_e32 v120, v125, v125
	v_max_f32_e32 v121, 0, v121
	v_max_f32_e32 v122, 0, v122
	v_lshl_add_u64 v[142:143], v[142:143], 0, s[52:53]
	v_max_f32_e32 v124, v124, v124
	v_max_f32_e32 v120, 0, v120
	v_mul_f32_e32 v125, v121, v121
	v_max_f32_e32 v121, v126, v126
	v_mul_f32_e32 v126, v122, v122
	v_max_f32_e32 v122, v127, v127
	v_max_f32_e32 v123, v123, v123
	v_lshl_add_u64 v[142:143], v[142:143], 0, s[6:7]
	v_max_f32_e32 v124, 0, v124
	v_mul_f32_e32 v120, v120, v120
	v_max_f32_e32 v121, 0, v121
	v_max_f32_e32 v122, 0, v122
	v_max_f32_e32 v123, 0, v123
	v_max_f32_e32 v112, v112, v112
	v_lshl_add_u64 v[142:143], v[142:143], 0, v[132:133]
	v_mul_f32_e32 v124, v124, v124
	v_mul_f32_e32 v121, v121, v121
	v_mul_f32_e32 v122, v122, v122
	v_mul_f32_e32 v123, v123, v123
	v_cvt_pk_bf16_f32 v120, v124, v120
	v_max_f32_e32 v112, 0, v112
	v_max_f32_e32 v113, v113, v113
	v_max_f32_e32 v114, v114, v114
	v_cvt_pk_bf16_f32 v121, v121, v122
	v_cvt_pk_bf16_f32 v122, v149, v125
	v_cvt_pk_bf16_f32 v123, v126, v123
	global_store_dwordx4 v[142:143], v[120:123], off
	v_max_f32_e32 v113, 0, v113
	v_max_f32_e32 v114, 0, v114
	v_mul_f32_e32 v120, v112, v112
	v_max_f32_e32 v112, v117, v117
	v_max_f32_e32 v116, v116, v116
	v_max_f32_e32 v112, 0, v112
	v_mul_f32_e32 v117, v113, v113
	v_max_f32_e32 v113, v118, v118
	v_mul_f32_e32 v118, v114, v114
	v_max_f32_e32 v114, v119, v119
	v_max_f32_e32 v115, v115, v115
	v_max_f32_e32 v116, 0, v116
	v_mul_f32_e32 v112, v112, v112
	v_max_f32_e32 v113, 0, v113
	v_max_f32_e32 v114, 0, v114
	v_max_f32_e32 v115, 0, v115
	v_mul_f32_e32 v116, v116, v116
	v_mul_f32_e32 v113, v113, v113
	v_mul_f32_e32 v114, v114, v114
	v_mul_f32_e32 v115, v115, v115
	v_cvt_pk_bf16_f32 v112, v116, v112
	v_cvt_pk_bf16_f32 v113, v113, v114
	v_cvt_pk_bf16_f32 v114, v120, v117
	v_cvt_pk_bf16_f32 v115, v118, v115
	global_store_dwordx4 v[142:143], v[112:115], off offset:256
	v_max_f32_e32 v104, v104, v104
	v_max_f32_e32 v104, 0, v104
	v_or_b32_e32 v112, 16, v150
	v_ashrrev_i32_e32 v113, 31, v112
	v_lshlrev_b64 v[112:113], 13, v[112:113]
	v_max_f32_e32 v105, v105, v105
	v_max_f32_e32 v106, v106, v106
	v_lshl_add_u64 v[112:113], s[30:31], 0, v[112:113]
	v_mul_f32_e32 v114, v104, v104
	v_max_f32_e32 v104, v109, v109
	v_max_f32_e32 v105, 0, v105
	v_max_f32_e32 v106, 0, v106
	v_lshl_add_u64 v[112:113], v[112:113], 0, s[52:53]
	v_max_f32_e32 v108, v108, v108
	v_max_f32_e32 v104, 0, v104
	v_mul_f32_e32 v109, v105, v105
; __device__ __forceinline__ void st_bf16x8(bf16_t* p, const f32x4 a, const f32x4 b) { uint4 o; o.x = cvt_pk_bf16(a[0], a[1]); o.y = cvt_pk_bf16(a[2], a[3]); o.z = cvt_pk_bf16(b[0], b[1]); o.w = cvt_pk_bf16(b[2], b[3]); *(uint4*)p = o; }
;     __device__ __forceinline__ void row(const f32x4 (&a)[2][2], int row, int pn, int wc, int fq) const {
;         bf16_t* rp = T + (size_t)row * DFF + pn * BM + wc * 32 + 8 * fq;
; #pragma unroll
;         for (int bj = 0; bj < 2; ++bj) { f32x4 v0 = a[bj][0], v1 = a[bj][1];
; #pragma unroll
;             for (int j = 0; j < 4; ++j) { const float r0 = fmaxf(v0[j], 0.f), r1 = fmaxf(v1[j], 0.f); v0[j] = r0 * r0; v1[j] = r1 * r1; }
;             st_bf16x8(rp + bj * HALF, v0, v1); }
	v_max_f32_e32 v105, v110, v110
	v_mul_f32_e32 v110, v106, v106
	v_max_f32_e32 v106, v111, v111
	v_max_f32_e32 v107, v107, v107
	v_lshl_add_u64 v[112:113], v[112:113], 0, s[6:7]
	v_max_f32_e32 v108, 0, v108
	v_mul_f32_e32 v104, v104, v104
	v_max_f32_e32 v105, 0, v105
	v_max_f32_e32 v106, 0, v106
	v_max_f32_e32 v107, 0, v107
	v_max_f32_e32 v96, v96, v96
	v_lshl_add_u64 v[112:113], v[112:113], 0, v[132:133]
	v_mul_f32_e32 v108, v108, v108
	v_mul_f32_e32 v105, v105, v105
	v_mul_f32_e32 v106, v106, v106
	v_mul_f32_e32 v107, v107, v107
	v_cvt_pk_bf16_f32 v104, v108, v104
	v_max_f32_e32 v96, 0, v96
	v_max_f32_e32 v97, v97, v97
	v_max_f32_e32 v98, v98, v98
	v_cvt_pk_bf16_f32 v105, v105, v106
	v_cvt_pk_bf16_f32 v106, v114, v109
	v_cvt_pk_bf16_f32 v107, v110, v107
	global_store_dwordx4 v[112:113], v[104:107], off
	v_max_f32_e32 v97, 0, v97
	v_max_f32_e32 v98, 0, v98
	v_mul_f32_e32 v104, v96, v96
	v_max_f32_e32 v96, v101, v101
	v_max_f32_e32 v100, v100, v100
	v_max_f32_e32 v96, 0, v96
	v_mul_f32_e32 v101, v97, v97
	v_max_f32_e32 v97, v102, v102
	v_mul_f32_e32 v102, v98, v98
	v_max_f32_e32 v98, v103, v103
	v_max_f32_e32 v99, v99, v99
	v_max_f32_e32 v100, 0, v100
	v_mul_f32_e32 v96, v96, v96
	v_max_f32_e32 v97, 0, v97
	v_max_f32_e32 v98, 0, v98
	v_max_f32_e32 v99, 0, v99
	v_mul_f32_e32 v100, v100, v100
	v_mul_f32_e32 v97, v97, v97
	v_mul_f32_e32 v98, v98, v98
	v_mul_f32_e32 v99, v99, v99
	v_cvt_pk_bf16_f32 v96, v100, v96
	v_cvt_pk_bf16_f32 v97, v97, v98
	v_cvt_pk_bf16_f32 v98, v104, v101
	v_cvt_pk_bf16_f32 v99, v102, v99
	global_store_dwordx4 v[112:113], v[96:99], off offset:256
	v_max_f32_e32 v88, v88, v88
	v_max_f32_e32 v88, 0, v88
	v_or_b32_e32 v96, 32, v150
	v_ashrrev_i32_e32 v97, 31, v96
	v_lshlrev_b64 v[96:97], 13, v[96:97]
	v_max_f32_e32 v89, v89, v89
	v_max_f32_e32 v90, v90, v90
	v_lshl_add_u64 v[96:97], s[30:31], 0, v[96:97]
	v_mul_f32_e32 v98, v88, v88
	v_max_f32_e32 v88, v93, v93
	v_max_f32_e32 v89, 0, v89
	v_max_f32_e32 v90, 0, v90
	v_lshl_add_u64 v[96:97], v[96:97], 0, s[52:53]
	v_max_f32_e32 v92, v92, v92
	v_max_f32_e32 v88, 0, v88
	v_mul_f32_e32 v93, v89, v89
	v_max_f32_e32 v89, v94, v94
	v_mul_f32_e32 v94, v90, v90
	v_max_f32_e32 v90, v95, v95
	v_max_f32_e32 v91, v91, v91
	v_lshl_add_u64 v[96:97], v[96:97], 0, s[6:7]
	v_max_f32_e32 v92, 0, v92
	v_mul_f32_e32 v88, v88, v88
	v_max_f32_e32 v89, 0, v89
	v_max_f32_e32 v90, 0, v90
	v_max_f32_e32 v91, 0, v91
	v_max_f32_e32 v80, v80, v80
	v_lshl_add_u64 v[96:97], v[96:97], 0, v[132:133]
	v_mul_f32_e32 v92, v92, v92
	v_mul_f32_e32 v89, v89, v89
	v_mul_f32_e32 v90, v90, v90
	v_mul_f32_e32 v91, v91, v91
	v_cvt_pk_bf16_f32 v88, v92, v88
	v_max_f32_e32 v80, 0, v80
	v_max_f32_e32 v81, v81, v81
	v_max_f32_e32 v82, v82, v82
	v_cvt_pk_bf16_f32 v89, v89, v90
	v_cvt_pk_bf16_f32 v90, v98, v93
	v_cvt_pk_bf16_f32 v91, v94, v91
	global_store_dwordx4 v[96:97], v[88:91], off
	v_max_f32_e32 v81, 0, v81
	v_max_f32_e32 v82, 0, v82
	v_mul_f32_e32 v88, v80, v80
	v_max_f32_e32 v80, v85, v85
	v_max_f32_e32 v84, v84, v84
	v_max_f32_e32 v80, 0, v80
	v_mul_f32_e32 v85, v81, v81
	v_max_f32_e32 v81, v86, v86
	v_mul_f32_e32 v86, v82, v82
	v_max_f32_e32 v82, v87, v87
	v_max_f32_e32 v83, v83, v83
	v_max_f32_e32 v84, 0, v84
	v_mul_f32_e32 v80, v80, v80
	v_max_f32_e32 v81, 0, v81
	v_max_f32_e32 v82, 0, v82
	v_max_f32_e32 v83, 0, v83
	v_mul_f32_e32 v84, v84, v84
	v_mul_f32_e32 v81, v81, v81
	v_mul_f32_e32 v82, v82, v82
	v_mul_f32_e32 v83, v83, v83
	v_cvt_pk_bf16_f32 v80, v84, v80
	v_cvt_pk_bf16_f32 v81, v81, v82
	v_cvt_pk_bf16_f32 v82, v88, v85
	v_cvt_pk_bf16_f32 v83, v86, v83
	global_store_dwordx4 v[96:97], v[80:83], off offset:256
	v_max_f32_e32 v72, v72, v72
	v_max_f32_e32 v72, 0, v72
	v_or_b32_e32 v80, 48, v150
	v_ashrrev_i32_e32 v81, 31, v80
	v_lshlrev_b64 v[80:81], 13, v[80:81]
	v_max_f32_e32 v73, v73, v73
	v_max_f32_e32 v74, v74, v74
	v_lshl_add_u64 v[80:81], s[30:31], 0, v[80:81]
	v_mul_f32_e32 v82, v72, v72
	v_max_f32_e32 v72, v77, v77
	v_max_f32_e32 v73, 0, v73
	v_max_f32_e32 v74, 0, v74
	v_lshl_add_u64 v[80:81], v[80:81], 0, s[52:53]
	v_max_f32_e32 v76, v76, v76
	v_max_f32_e32 v72, 0, v72
	v_mul_f32_e32 v77, v73, v73
	v_max_f32_e32 v73, v78, v78
	v_mul_f32_e32 v78, v74, v74
	v_max_f32_e32 v74, v79, v79
	v_max_f32_e32 v75, v75, v75
	v_lshl_add_u64 v[80:81], v[80:81], 0, s[6:7]
	v_max_f32_e32 v76, 0, v76
	v_mul_f32_e32 v72, v72, v72
	v_max_f32_e32 v73, 0, v73
	v_max_f32_e32 v74, 0, v74
	v_max_f32_e32 v75, 0, v75
	v_max_f32_e32 v64, v64, v64
	v_max_f32_e32 v65, v65, v65
	v_max_f32_e32 v66, v66, v66
	v_lshl_add_u64 v[80:81], v[80:81], 0, v[132:133]
	v_mul_f32_e32 v76, v76, v76
	v_mul_f32_e32 v73, v73, v73
	v_mul_f32_e32 v74, v74, v74
	v_mul_f32_e32 v75, v75, v75
	v_cvt_pk_bf16_f32 v72, v76, v72
	v_max_f32_e32 v64, 0, v64
	v_max_f32_e32 v65, 0, v65
	v_max_f32_e32 v66, 0, v66
	v_cvt_pk_bf16_f32 v73, v73, v74
	v_cvt_pk_bf16_f32 v74, v82, v77
	v_cvt_pk_bf16_f32 v75, v78, v75
	global_store_dwordx4 v[80:81], v[72:75], off
	v_max_f32_e32 v67, v67, v67
	v_max_f32_e32 v68, v68, v68
	v_mul_f32_e32 v72, v64, v64
	v_max_f32_e32 v64, v69, v69
	v_mul_f32_e32 v69, v65, v65
	v_max_f32_e32 v65, v70, v70
	v_mul_f32_e32 v70, v66, v66
	v_max_f32_e32 v66, v71, v71
	v_max_f32_e32 v65, 0, v65
	v_max_f32_e32 v66, 0, v66
	v_max_f32_e32 v64, 0, v64
	v_mul_f32_e32 v65, v65, v65
	v_max_f32_e32 v67, 0, v67
	v_mul_f32_e32 v66, v66, v66
	v_max_f32_e32 v56, v56, v56
	v_max_f32_e32 v68, 0, v68
	v_mul_f32_e32 v64, v64, v64
	v_mul_f32_e32 v67, v67, v67
	v_cvt_pk_bf16_f32 v65, v65, v66
	v_cvt_pk_bf16_f32 v66, v72, v69
	v_max_f32_e32 v56, 0, v56
	v_max_f32_e32 v57, v57, v57
	v_max_f32_e32 v58, v58, v58
	v_mul_f32_e32 v68, v68, v68
	v_cvt_pk_bf16_f32 v64, v68, v64
; __device__ __forceinline__ void st_bf16x8(bf16_t* p, const f32x4 a, const f32x4 b) { uint4 o; o.x = cvt_pk_bf16(a[0], a[1]); o.y = cvt_pk_bf16(a[2], a[3]); o.z = cvt_pk_bf16(b[0], b[1]); o.w = cvt_pk_bf16(b[2], b[3]); *(uint4*)p = o; }
;     __device__ __forceinline__ void row(const f32x4 (&a)[2][2], int row, int pn, int wc, int fq) const {
;         bf16_t* rp = T + (size_t)row * DFF + pn * BM + wc * 32 + 8 * fq;
; #pragma unroll
;         for (int bj = 0; bj < 2; ++bj) { f32x4 v0 = a[bj][0], v1 = a[bj][1];
; #pragma unroll
;             for (int j = 0; j < 4; ++j) { const float r0 = fmaxf(v0[j], 0.f), r1 = fmaxf(v1[j], 0.f); v0[j] = r0 * r0; v1[j] = r1 * r1; }
;             st_bf16x8(rp + bj * HALF, v0, v1); }
	v_cvt_pk_bf16_f32 v67, v70, v67
	global_store_dwordx4 v[80:81], v[64:67], off offset:256
	v_max_f32_e32 v60, v60, v60
	v_max_f32_e32 v57, 0, v57
	v_mul_f32_e32 v66, v56, v56
	v_max_f32_e32 v56, v61, v61
	v_max_f32_e32 v58, 0, v58
	v_max_f32_e32 v60, 0, v60
	v_max_f32_e32 v56, 0, v56
	v_mul_f32_e32 v61, v57, v57
	v_max_f32_e32 v57, v62, v62
	v_mul_f32_e32 v62, v58, v58
	v_max_f32_e32 v58, v63, v63
	v_mul_f32_e32 v60, v60, v60
	v_mul_f32_e32 v56, v56, v56
	v_max_f32_e32 v57, 0, v57
	v_max_f32_e32 v58, 0, v58
	v_max_f32_e32 v59, v59, v59
	v_mul_f32_e32 v57, v57, v57
	v_max_f32_e32 v59, 0, v59
	v_mul_f32_e32 v58, v58, v58
	v_cvt_pk_bf16_f32 v56, v60, v56
	v_add_co_u32_e32 v60, vcc, s76, v142
	v_max_f32_e32 v48, v48, v48
	v_max_f32_e32 v49, v49, v49
	v_max_f32_e32 v50, v50, v50
	v_mul_f32_e32 v59, v59, v59
	v_cvt_pk_bf16_f32 v57, v57, v58
	v_cvt_pk_bf16_f32 v58, v66, v61
	v_addc_co_u32_e32 v61, vcc, 0, v143, vcc
	v_max_f32_e32 v48, 0, v48
	v_max_f32_e32 v49, 0, v49
	v_max_f32_e32 v50, 0, v50
	v_cvt_pk_bf16_f32 v59, v62, v59
	global_store_dwordx4 v[60:61], v[56:59], off
	v_max_f32_e32 v51, v51, v51
	v_max_f32_e32 v52, v52, v52
	v_mul_f32_e32 v56, v48, v48
	v_max_f32_e32 v48, v53, v53
	v_mul_f32_e32 v53, v49, v49
	v_max_f32_e32 v49, v54, v54
	v_mul_f32_e32 v54, v50, v50
	v_max_f32_e32 v50, v55, v55
	v_max_f32_e32 v49, 0, v49
	v_max_f32_e32 v50, 0, v50
	v_max_f32_e32 v48, 0, v48
	v_mul_f32_e32 v49, v49, v49
	v_max_f32_e32 v51, 0, v51
	v_mul_f32_e32 v50, v50, v50
	v_max_f32_e32 v40, v40, v40
	v_lshl_add_u64 v[64:65], v[142:143], 0, s[8:9]
	v_max_f32_e32 v52, 0, v52
	v_mul_f32_e32 v48, v48, v48
	v_mul_f32_e32 v51, v51, v51
	v_cvt_pk_bf16_f32 v49, v49, v50
	v_cvt_pk_bf16_f32 v50, v56, v53
	v_max_f32_e32 v40, 0, v40
	v_max_f32_e32 v41, v41, v41
	v_max_f32_e32 v42, v42, v42
	v_mul_f32_e32 v52, v52, v52
	v_cvt_pk_bf16_f32 v48, v52, v48
	v_cvt_pk_bf16_f32 v51, v54, v51
	global_store_dwordx4 v[64:65], v[48:51], off offset:256
	v_max_f32_e32 v44, v44, v44
	v_max_f32_e32 v41, 0, v41
	v_mul_f32_e32 v50, v40, v40
	v_max_f32_e32 v40, v45, v45
	v_max_f32_e32 v42, 0, v42
	v_max_f32_e32 v44, 0, v44
	v_max_f32_e32 v40, 0, v40
	v_mul_f32_e32 v45, v41, v41
	v_max_f32_e32 v41, v46, v46
	v_mul_f32_e32 v46, v42, v42
	v_max_f32_e32 v42, v47, v47
	v_mul_f32_e32 v44, v44, v44
	v_mul_f32_e32 v40, v40, v40
	v_max_f32_e32 v41, 0, v41
	v_max_f32_e32 v42, 0, v42
	v_max_f32_e32 v43, v43, v43
	v_mul_f32_e32 v41, v41, v41
	v_max_f32_e32 v43, 0, v43
	v_mul_f32_e32 v42, v42, v42
	v_cvt_pk_bf16_f32 v40, v44, v40
	v_add_co_u32_e32 v44, vcc, s77, v142
	v_max_f32_e32 v32, v32, v32
	v_max_f32_e32 v33, v33, v33
	v_max_f32_e32 v34, v34, v34
	v_mul_f32_e32 v43, v43, v43
	v_cvt_pk_bf16_f32 v41, v41, v42
	v_cvt_pk_bf16_f32 v42, v50, v45
	v_addc_co_u32_e32 v45, vcc, 0, v143, vcc
	v_max_f32_e32 v32, 0, v32
	v_max_f32_e32 v33, 0, v33
	v_max_f32_e32 v34, 0, v34
	v_cvt_pk_bf16_f32 v43, v46, v43
	global_store_dwordx4 v[44:45], v[40:43], off
	v_max_f32_e32 v35, v35, v35
	v_max_f32_e32 v36, v36, v36
	v_mul_f32_e32 v40, v32, v32
	v_max_f32_e32 v32, v37, v37
	v_mul_f32_e32 v37, v33, v33
	v_max_f32_e32 v33, v38, v38
	v_mul_f32_e32 v38, v34, v34
	v_max_f32_e32 v34, v39, v39
	v_max_f32_e32 v33, 0, v33
	v_max_f32_e32 v34, 0, v34
	v_max_f32_e32 v32, 0, v32
	v_mul_f32_e32 v33, v33, v33
	v_max_f32_e32 v35, 0, v35
	v_mul_f32_e32 v34, v34, v34
	v_max_f32_e32 v24, v24, v24
	v_lshl_add_u64 v[48:49], v[142:143], 0, s[28:29]
	v_max_f32_e32 v36, 0, v36
	v_mul_f32_e32 v32, v32, v32
	v_mul_f32_e32 v35, v35, v35
	v_cvt_pk_bf16_f32 v33, v33, v34
	v_cvt_pk_bf16_f32 v34, v40, v37
	v_max_f32_e32 v24, 0, v24
	v_max_f32_e32 v25, v25, v25
	v_max_f32_e32 v26, v26, v26
	v_mul_f32_e32 v36, v36, v36
	v_cvt_pk_bf16_f32 v32, v36, v32
	v_cvt_pk_bf16_f32 v35, v38, v35
; __device__ __forceinline__ void st_bf16x8(bf16_t* p, const f32x4 a, const f32x4 b) { uint4 o; o.x = cvt_pk_bf16(a[0], a[1]); o.y = cvt_pk_bf16(a[2], a[3]); o.z = cvt_pk_bf16(b[0], b[1]); o.w = cvt_pk_bf16(b[2], b[3]); *(uint4*)p = o; }
; #define PG8_WAIT_V(n) asm volatile("s_waitcnt vmcnt(" #n ")" ::: "memory")
; #define PG8_BAR __builtin_amdgcn_s_barrier()
;     __device__ __forceinline__ void row(const f32x4 (&a)[2][2], int row, int pn, int wc, int fq) const {
;         bf16_t* rp = T + (size_t)row * DFF + pn * BM + wc * 32 + 8 * fq;
; #pragma unroll
;         for (int bj = 0; bj < 2; ++bj) { f32x4 v0 = a[bj][0], v1 = a[bj][1];
; #pragma unroll
;             for (int j = 0; j < 4; ++j) { const float r0 = fmaxf(v0[j], 0.f), r1 = fmaxf(v1[j], 0.f); v0[j] = r0 * r0; v1[j] = r1 * r1; }
;             st_bf16x8(rp + bj * HALF, v0, v1); }
; template <class Epi>
; __device__ __forceinline__ void gemm_phase(LAS unsigned char* lds, const Gemm g, const StaticOrder& S, const Epi& E, float* smem = nullptr) {
;     ...
;         if constexpr (!Epi::AFTER_DRAIN) E(acc, cur, wr, wc, fr, fq);
;         if (!has_next) break;
; #pragma unroll
;         for (int a = 0; a < 2; ++a)
; #pragma unroll
;             for (int b = 0; b < 2; ++b)
; #pragma unroll
;                 for (int m = 0; m < 4; ++m)
; #pragma unroll
;                     for (int n = 0; n < 2; ++n) acc[a][b][m][n] = (f32x4){0.f, 0.f, 0.f, 0.f};
;         cur = nxt; cA = nA; cB = nB; ++ui;
;     }
;     PG8_WAIT_V(0);
;     if (wr == 0) PG8_BAR;
;     PG8_BAR;
	global_store_dwordx4 v[48:49], v[32:35], off offset:256
	v_max_f32_e32 v28, v28, v28
	v_max_f32_e32 v25, 0, v25
	v_mul_f32_e32 v34, v24, v24
	v_max_f32_e32 v24, v29, v29
	v_max_f32_e32 v26, 0, v26
	v_max_f32_e32 v28, 0, v28
	v_max_f32_e32 v24, 0, v24
	v_mul_f32_e32 v29, v25, v25
	v_max_f32_e32 v25, v30, v30
	v_mul_f32_e32 v30, v26, v26
	v_max_f32_e32 v26, v31, v31
	v_mul_f32_e32 v28, v28, v28
	v_mul_f32_e32 v24, v24, v24
	v_max_f32_e32 v25, 0, v25
	v_max_f32_e32 v26, 0, v26
	v_max_f32_e32 v27, v27, v27
	v_mul_f32_e32 v25, v25, v25
	v_max_f32_e32 v27, 0, v27
	v_mul_f32_e32 v26, v26, v26
	v_cvt_pk_bf16_f32 v24, v28, v24
	v_add_co_u32_e32 v28, vcc, s78, v142
	v_max_f32_e32 v16, v16, v16
	v_max_f32_e32 v17, v17, v17
	v_max_f32_e32 v18, v18, v18
	v_mul_f32_e32 v27, v27, v27
	v_cvt_pk_bf16_f32 v25, v25, v26
	v_cvt_pk_bf16_f32 v26, v34, v29
	v_addc_co_u32_e32 v29, vcc, 0, v143, vcc
	v_max_f32_e32 v16, 0, v16
	v_max_f32_e32 v17, 0, v17
	v_max_f32_e32 v18, 0, v18
	v_cvt_pk_bf16_f32 v27, v30, v27
	global_store_dwordx4 v[28:29], v[24:27], off
	v_max_f32_e32 v19, v19, v19
	v_max_f32_e32 v20, v20, v20
	v_mul_f32_e32 v24, v16, v16
	v_max_f32_e32 v16, v21, v21
	v_mul_f32_e32 v21, v17, v17
	v_max_f32_e32 v17, v22, v22
	v_mul_f32_e32 v22, v18, v18
	v_max_f32_e32 v18, v23, v23
	v_max_f32_e32 v17, 0, v17
	v_max_f32_e32 v18, 0, v18
	v_max_f32_e32 v16, 0, v16
	v_mul_f32_e32 v17, v17, v17
	v_max_f32_e32 v19, 0, v19
	v_mul_f32_e32 v18, v18, v18
	v_max_f32_e32 v8, v8, v8
	v_lshl_add_u64 v[32:33], v[142:143], 0, s[36:37]
	v_max_f32_e32 v20, 0, v20
	v_mul_f32_e32 v16, v16, v16
	v_mul_f32_e32 v19, v19, v19
	v_cvt_pk_bf16_f32 v17, v17, v18
	v_cvt_pk_bf16_f32 v18, v24, v21
	v_max_f32_e32 v8, 0, v8
	v_max_f32_e32 v9, v9, v9
	v_max_f32_e32 v10, v10, v10
	v_mul_f32_e32 v20, v20, v20
	v_cvt_pk_bf16_f32 v16, v20, v16
	v_cvt_pk_bf16_f32 v19, v22, v19
	global_store_dwordx4 v[32:33], v[16:19], off offset:256
	v_max_f32_e32 v12, v12, v12
	v_max_f32_e32 v9, 0, v9
	v_mul_f32_e32 v18, v8, v8
	v_max_f32_e32 v8, v13, v13
	v_max_f32_e32 v10, 0, v10
	v_max_f32_e32 v12, 0, v12
	v_max_f32_e32 v8, 0, v8
	v_mul_f32_e32 v13, v9, v9
	v_max_f32_e32 v9, v14, v14
	v_mul_f32_e32 v14, v10, v10
	v_max_f32_e32 v10, v15, v15
	v_mul_f32_e32 v12, v12, v12
	v_mul_f32_e32 v8, v8, v8
	v_max_f32_e32 v9, 0, v9
	v_max_f32_e32 v10, 0, v10
	v_max_f32_e32 v11, v11, v11
	v_mul_f32_e32 v9, v9, v9
	v_max_f32_e32 v11, 0, v11
	v_mul_f32_e32 v10, v10, v10
	v_cvt_pk_bf16_f32 v8, v12, v8
	v_add_co_u32_e32 v12, vcc, s79, v142
	v_max_f32_e32 v0, v0, v0
	v_max_f32_e32 v1, v1, v1
	v_max_f32_e32 v2, v2, v2
	v_mul_f32_e32 v11, v11, v11
	v_cvt_pk_bf16_f32 v9, v9, v10
	v_cvt_pk_bf16_f32 v10, v18, v13
	v_addc_co_u32_e32 v13, vcc, 0, v143, vcc
	v_max_f32_e32 v0, 0, v0
	v_max_f32_e32 v1, 0, v1
	v_max_f32_e32 v2, 0, v2
	v_cvt_pk_bf16_f32 v11, v14, v11
	global_store_dwordx4 v[12:13], v[8:11], off
	v_max_f32_e32 v3, v3, v3
	v_max_f32_e32 v4, v4, v4
	v_mul_f32_e32 v8, v0, v0
	v_max_f32_e32 v0, v5, v5
	v_mul_f32_e32 v5, v1, v1
	v_max_f32_e32 v1, v6, v6
	v_mul_f32_e32 v6, v2, v2
	v_max_f32_e32 v2, v7, v7
	v_max_f32_e32 v0, 0, v0
	v_max_f32_e32 v1, 0, v1
	v_max_f32_e32 v2, 0, v2
	v_max_f32_e32 v3, 0, v3
	v_lshl_add_u64 v[16:17], v[142:143], 0, s[38:39]
	v_max_f32_e32 v4, 0, v4
	v_mul_f32_e32 v0, v0, v0
	v_mul_f32_e32 v1, v1, v1
	v_mul_f32_e32 v2, v2, v2
	v_mul_f32_e32 v3, v3, v3
	s_and_b64 vcc, exec, s[4:5]
	s_mov_b32 s53, s44
	s_mov_b32 s52, s46
	s_mov_b64 s[64:65], s[50:51]
	s_mov_b64 s[62:63], s[48:49]
	v_mul_f32_e32 v4, v4, v4
	v_cvt_pk_bf16_f32 v0, v4, v0
	v_cvt_pk_bf16_f32 v1, v1, v2
	v_cvt_pk_bf16_f32 v2, v8, v5
	v_cvt_pk_bf16_f32 v3, v6, v3
	global_store_dwordx4 v[16:17], v[0:3], off offset:256
	s_cbranch_vccz .LBB0_661
	s_waitcnt vmcnt(0)
	s_cmpk_gt_u32 s12, 0xff
	s_cbranch_scc1 .LBB0_672
	s_barrier

; #define PG8_STAGE(bufoff, gbase, voff) do { _Pragma("unroll") for (int _i = 0; _i < 2; ++_i) \
;         __builtin_amdgcn_global_load_lds((const unsigned*)((const char*)(gbase) + (voff)[_i]), (LAS unsigned*)(lds + (bufoff) + ldsw + _i * 8192), 16, 0, 0); } while (0)
; #define PG8_LDA(dst, b, h) do { _Pragma("unroll") for (int m = 0; m < 4; ++m) _Pragma("unroll") for (int k = 0; k < 2; ++k) dst[m][k] = *(const LAS bf16x8*)(lds + PG8_SA(b, h) + aoff + m * 2048 + k * 1024); } while (0)
; #define PG8_LDB(dst, b, h) do { _Pragma("unroll") for (int n = 0; n < 2; ++n) _Pragma("unroll") for (int k = 0; k < 2; ++k) dst[n][k] = *(const LAS bf16x8*)(lds + PG8_SB(b, h) + boff + n * 2048 + k * 1024); } while (0)
; #define PG8_MMA(ai, bj, At, Bt) do { __builtin_amdgcn_s_setprio(1); _Pragma("unroll") for (int m = 0; m < 4; ++m) _Pragma("unroll") for (int n = 0; n < 2; ++n) _Pragma("unroll") for (int k = 0; k < 2; ++k) \
;         acc[ai][bj][m][n] = __builtin_amdgcn_mfma_f32_16x16x32_bf16(Bt[n][k], At[m][k], acc[ai][bj][m][n], 0, 0, 0); __builtin_amdgcn_s_setprio(0); } while (0)
; #define PG8_WAIT_L(n) asm volatile("s_waitcnt lgkmcnt(" #n ")" ::: "memory")
; #define PG8_BAR __builtin_amdgcn_s_barrier()
; #define PG8_SCHED __builtin_amdgcn_sched_barrier(0)
; template <class Epi>
; __device__ __forceinline__ void gemm_phase(LAS unsigned char* lds, const Gemm g, const StaticOrder& S, const Epi& E, float* smem = nullptr) {
;     ...
;             const char* a1 = cA + (size_t)(t + 1) * kstep;
;             const char* a2 = last ? nA : cA + (size_t)(t + 2) * kstep; const char* b2 = last ? nB : cB + (size_t)(t + 2) * kstep;
;             const char* a3 = a2 + kstep; const char* b3 = b2 + kstep;
;             PG8_LDB(B0, 0, 0); PG8_SCHED; PG8_LDA(At, 0, 0); PG8_STAGE(PG8_SA(1, 1), a1 + hstep, voffA);
;             PG8_WAIT_L(8); PG8_BAR; PG8_WAIT_L(0); PG8_MMA(0, 0, At, B0); PG8_BAR; PG8_SCHED;
;             PG8_LDB(B1, 0, 1); PG8_STAGE(PG8_SB(0, 0), b2, voffA);
;             PG8_BAR; PG8_WAIT_L(0); PG8_MMA(0, 1, At, B1); PG8_BAR;
;             PG8_LDA(At, 0, 1); PG8_STAGE(PG8_SA(0, 0), a2, voffA);
;             PG8_BAR; PG8_WAIT_L(0); PG8_MMA(1, 0, At, B0); PG8_BAR; PG8_SCHED;
.LBB0_774:
	v_add_u32_e32 v158, s50, v144
	s_add_u32 s36, s10, s28
	ds_read_b128 v[146:149], v158
	ds_read_b128 v[150:153], v158 offset:1024
	ds_read_b128 v[154:157], v158 offset:2048
	ds_read_b128 v[158:161], v158 offset:3072
	s_addc_u32 s37, s11, s29
	s_add_u32 s36, s36, 0x100
	s_addc_u32 s37, s37, 0
	s_add_u32 s64, s53, s28
	s_addc_u32 s65, s60, s29
	s_cmpk_eq_i32 s28, 0x1f00
	s_cselect_b32 s39, s23, s37
	s_cselect_b32 s38, s61, s36
	s_cselect_b32 s37, s15, s65
	s_cselect_b32 s36, s62, s64
	v_lshl_add_u64 v[170:171], v[140:141], 0, s[28:29]
	s_add_i32 m0, s43, 0xc000
	ds_read_b128 v[162:165], v145
	ds_read_b128 v[166:169], v145 offset:1024
	ds_read_b128 v[174:177], v145 offset:2048
	ds_read_b128 v[178:181], v145 offset:3072
	ds_read_b128 v[186:189], v145 offset:4096
	ds_read_b128 v[190:193], v145 offset:5120
	ds_read_b128 v[194:197], v145 offset:6144
	ds_read_b128 v[198:201], v145 offset:7168
	global_load_lds_dwordx4 v[170:171], off
	v_lshl_add_u64 v[170:171], v[142:143], 0, s[28:29]
	s_add_i32 m0, s43, 0xe000
	s_nop 0
	global_load_lds_dwordx4 v[170:171], off
	s_waitcnt lgkmcnt(8)
	s_barrier
	s_waitcnt lgkmcnt(0)
	s_waitcnt lgkmcnt(0)
	v_mfma_f32_16x16x32_bf16 v[124:127], v[146:149], v[162:165], v[124:127]
	v_mfma_f32_16x16x32_bf16 v[120:123], v[154:157], v[162:165], v[120:123]
	v_mfma_f32_16x16x32_bf16 v[108:111], v[146:149], v[174:177], v[108:111]
	v_mfma_f32_16x16x32_bf16 v[104:107], v[154:157], v[174:177], v[104:107]
	v_mfma_f32_16x16x32_bf16 v[92:95], v[146:149], v[186:189], v[92:95]
	v_mfma_f32_16x16x32_bf16 v[88:91], v[154:157], v[186:189], v[88:91]
	v_mfma_f32_16x16x32_bf16 v[76:79], v[146:149], v[194:197], v[76:79]
	v_mfma_f32_16x16x32_bf16 v[72:75], v[154:157], v[194:197], v[72:75]
	v_mfma_f32_16x16x32_bf16 v[124:127], v[150:153], v[166:169], v[124:127]
	v_mfma_f32_16x16x32_bf16 v[120:123], v[158:161], v[166:169], v[120:123]
	v_mfma_f32_16x16x32_bf16 v[108:111], v[150:153], v[178:181], v[108:111]
	v_mfma_f32_16x16x32_bf16 v[104:107], v[158:161], v[178:181], v[104:107]
	v_mfma_f32_16x16x32_bf16 v[92:95], v[150:153], v[190:193], v[92:95]
	v_mfma_f32_16x16x32_bf16 v[88:91], v[158:161], v[190:193], v[88:91]
	v_mfma_f32_16x16x32_bf16 v[76:79], v[150:153], v[198:201], v[76:79]
	v_mfma_f32_16x16x32_bf16 v[72:75], v[158:161], v[198:201], v[72:75]
	s_barrier
	v_add_u32_e32 v170, s51, v144
	s_add_i32 s64, s50, s42
	ds_read_b128 v[202:205], v170
	ds_read_b128 v[206:209], v170 offset:1024
	ds_read_b128 v[210:213], v170 offset:2048
	ds_read_b128 v[214:217], v170 offset:3072
	v_lshl_add_u64 v[170:171], s[36:37], 0, v[128:129]
	s_mov_b32 m0, s64
	v_lshl_add_u64 v[182:183], s[36:37], 0, v[130:131]
	global_load_lds_dwordx4 v[170:171], off
	s_add_i32 m0, s64, 0x2000
	s_nop 0
	global_load_lds_dwordx4 v[182:183], off
	s_barrier
	s_waitcnt lgkmcnt(0)
	s_waitcnt lgkmcnt(0)
	v_mfma_f32_16x16x32_bf16 v[116:119], v[202:205], v[162:165], v[116:119]
	v_mfma_f32_16x16x32_bf16 v[112:115], v[210:213], v[162:165], v[112:115]
	v_mfma_f32_16x16x32_bf16 v[100:103], v[202:205], v[174:177], v[100:103]
	v_mfma_f32_16x16x32_bf16 v[96:99], v[210:213], v[174:177], v[96:99]
	v_mfma_f32_16x16x32_bf16 v[84:87], v[202:205], v[186:189], v[84:87]
	v_mfma_f32_16x16x32_bf16 v[80:83], v[210:213], v[186:189], v[80:83]
	v_mfma_f32_16x16x32_bf16 v[68:71], v[202:205], v[194:197], v[68:71]
	v_mfma_f32_16x16x32_bf16 v[64:67], v[210:213], v[194:197], v[64:67]
	v_mfma_f32_16x16x32_bf16 v[116:119], v[206:209], v[166:169], v[116:119]
	v_mfma_f32_16x16x32_bf16 v[112:115], v[214:217], v[166:169], v[112:115]
	v_mfma_f32_16x16x32_bf16 v[100:103], v[206:209], v[178:181], v[100:103]
	v_mfma_f32_16x16x32_bf16 v[96:99], v[214:217], v[178:181], v[96:99]
	v_mfma_f32_16x16x32_bf16 v[84:87], v[206:209], v[190:193], v[84:87]
	v_mfma_f32_16x16x32_bf16 v[80:83], v[214:217], v[190:193], v[80:83]
	v_mfma_f32_16x16x32_bf16 v[68:71], v[206:209], v[198:201], v[68:71]
	v_mfma_f32_16x16x32_bf16 v[64:67], v[214:217], v[198:201], v[64:67]
	s_mov_b32 m0, s43
	v_lshl_add_u64 v[218:219], s[38:39], 0, v[128:129]
	s_barrier
	ds_read_b128 v[162:165], v145 offset:16384
	ds_read_b128 v[166:169], v145 offset:17408
	ds_read_b128 v[174:177], v145 offset:18432
	ds_read_b128 v[178:181], v145 offset:19456
	ds_read_b128 v[186:189], v145 offset:20480
	ds_read_b128 v[190:193], v145 offset:21504
	ds_read_b128 v[194:197], v145 offset:22528
	ds_read_b128 v[198:201], v145 offset:23552
	global_load_lds_dwordx4 v[218:219], off
	v_lshl_add_u64 v[220:221], s[38:39], 0, v[130:131]
	s_mov_b32 m0, s44
	s_nop 0
	global_load_lds_dwordx4 v[220:221], off
	s_barrier
	s_waitcnt lgkmcnt(0)
	s_waitcnt lgkmcnt(0)
	v_mfma_f32_16x16x32_bf16 v[60:63], v[146:149], v[162:165], v[60:63]
	v_mfma_f32_16x16x32_bf16 v[56:59], v[154:157], v[162:165], v[56:59]
	v_mfma_f32_16x16x32_bf16 v[44:47], v[146:149], v[174:177], v[44:47]
	v_mfma_f32_16x16x32_bf16 v[40:43], v[154:157], v[174:177], v[40:43]
	v_mfma_f32_16x16x32_bf16 v[28:31], v[146:149], v[186:189], v[28:31]
	v_mfma_f32_16x16x32_bf16 v[24:27], v[154:157], v[186:189], v[24:27]
	v_mfma_f32_16x16x32_bf16 v[12:15], v[146:149], v[194:197], v[12:15]
	v_mfma_f32_16x16x32_bf16 v[8:11], v[154:157], v[194:197], v[8:11]
	v_mfma_f32_16x16x32_bf16 v[60:63], v[150:153], v[166:169], v[60:63]
	v_mfma_f32_16x16x32_bf16 v[56:59], v[158:161], v[166:169], v[56:59]
	v_mfma_f32_16x16x32_bf16 v[44:47], v[150:153], v[178:181], v[44:47]
	v_mfma_f32_16x16x32_bf16 v[40:43], v[158:161], v[178:181], v[40:43]
	v_mfma_f32_16x16x32_bf16 v[28:31], v[150:153], v[190:193], v[28:31]
	v_mfma_f32_16x16x32_bf16 v[24:27], v[158:161], v[190:193], v[24:27]
	v_mfma_f32_16x16x32_bf16 v[12:15], v[150:153], v[198:201], v[12:15]
	v_mfma_f32_16x16x32_bf16 v[8:11], v[158:161], v[198:201], v[8:11]
	s_barrier
; #define PG8_STAGE(bufoff, gbase, voff) do { _Pragma("unroll") for (int _i = 0; _i < 2; ++_i) \
;         __builtin_amdgcn_global_load_lds((const unsigned*)((const char*)(gbase) + (voff)[_i]), (LAS unsigned*)(lds + (bufoff) + ldsw + _i * 8192), 16, 0, 0); } while (0)
; #define PG8_LDA(dst, b, h) do { _Pragma("unroll") for (int m = 0; m < 4; ++m) _Pragma("unroll") for (int k = 0; k < 2; ++k) dst[m][k] = *(const LAS bf16x8*)(lds + PG8_SA(b, h) + aoff + m * 2048 + k * 1024); } while (0)
; #define PG8_LDB(dst, b, h) do { _Pragma("unroll") for (int n = 0; n < 2; ++n) _Pragma("unroll") for (int k = 0; k < 2; ++k) dst[n][k] = *(const LAS bf16x8*)(lds + PG8_SB(b, h) + boff + n * 2048 + k * 1024); } while (0)
; #define PG8_MMA(ai, bj, At, Bt) do { __builtin_amdgcn_s_setprio(1); _Pragma("unroll") for (int m = 0; m < 4; ++m) _Pragma("unroll") for (int n = 0; n < 2; ++n) _Pragma("unroll") for (int k = 0; k < 2; ++k) \
;         acc[ai][bj][m][n] = __builtin_amdgcn_mfma_f32_16x16x32_bf16(Bt[n][k], At[m][k], acc[ai][bj][m][n], 0, 0, 0); __builtin_amdgcn_s_setprio(0); } while (0)
; #define PG8_WAIT_V(n) asm volatile("s_waitcnt vmcnt(" #n ")" ::: "memory")
; #define PG8_WAIT_L(n) asm volatile("s_waitcnt lgkmcnt(" #n ")" ::: "memory")
; #define PG8_BAR __builtin_amdgcn_s_barrier()
; #define PG8_SCHED __builtin_amdgcn_sched_barrier(0)
; template <class Epi>
; __device__ __forceinline__ void gemm_phase(LAS unsigned char* lds, const Gemm g, const StaticOrder& S, const Epi& E, float* smem = nullptr) {
;     ...
;             PG8_STAGE(PG8_SB(0, 1), b2 + hstep, voffA);
;             PG8_WAIT_V(6); PG8_BAR; PG8_MMA(1, 1, At, B1); PG8_BAR;
;             PG8_LDB(B0, 1, 0); PG8_SCHED; PG8_LDA(At, 1, 0); PG8_STAGE(PG8_SA(0, 1), a2 + hstep, voffA);
;             PG8_WAIT_L(8); PG8_BAR; PG8_WAIT_L(0); PG8_MMA(0, 0, At, B0); PG8_BAR; PG8_SCHED;
;             PG8_LDB(B1, 1, 1); PG8_STAGE(PG8_SB(1, 0), b3, voffA);
;             PG8_BAR; PG8_WAIT_L(0); PG8_MMA(0, 1, At, B1); PG8_BAR;
;             PG8_LDA(At, 1, 1); PG8_STAGE(PG8_SA(1, 0), a3, voffA);
	s_add_u32 s64, s36, 0x100000
	s_addc_u32 s65, s37, 0
	s_add_i32 s66, s51, s42
	v_lshl_add_u64 v[146:147], s[64:65], 0, v[128:129]
	s_mov_b32 m0, s66
	s_nop 0
	global_load_lds_dwordx4 v[146:147], off
	v_lshl_add_u64 v[146:147], s[64:65], 0, v[130:131]
	s_add_i32 m0, s66, 0x2000
	s_nop 0
	global_load_lds_dwordx4 v[146:147], off
	s_waitcnt vmcnt(6)
	s_barrier
	v_mfma_f32_16x16x32_bf16 v[52:55], v[202:205], v[162:165], v[52:55]
	v_mfma_f32_16x16x32_bf16 v[48:51], v[210:213], v[162:165], v[48:51]
	v_mfma_f32_16x16x32_bf16 v[36:39], v[202:205], v[174:177], v[36:39]
	v_mfma_f32_16x16x32_bf16 v[32:35], v[210:213], v[174:177], v[32:35]
	v_mfma_f32_16x16x32_bf16 v[20:23], v[202:205], v[186:189], v[20:23]
	v_mfma_f32_16x16x32_bf16 v[16:19], v[210:213], v[186:189], v[16:19]
	v_mfma_f32_16x16x32_bf16 v[4:7], v[202:205], v[194:197], v[4:7]
	v_mfma_f32_16x16x32_bf16 v[0:3], v[210:213], v[194:197], v[0:3]
	v_mfma_f32_16x16x32_bf16 v[52:55], v[206:209], v[166:169], v[52:55]
	v_mfma_f32_16x16x32_bf16 v[48:51], v[214:217], v[166:169], v[48:51]
	v_mfma_f32_16x16x32_bf16 v[36:39], v[206:209], v[178:181], v[36:39]
	v_mfma_f32_16x16x32_bf16 v[32:35], v[214:217], v[178:181], v[32:35]
	v_mfma_f32_16x16x32_bf16 v[20:23], v[206:209], v[190:193], v[20:23]
	v_mfma_f32_16x16x32_bf16 v[16:19], v[214:217], v[190:193], v[16:19]
	v_mfma_f32_16x16x32_bf16 v[4:7], v[206:209], v[198:201], v[4:7]
	v_mfma_f32_16x16x32_bf16 v[0:3], v[214:217], v[198:201], v[0:3]
	s_add_i32 s64, 16, 0x18000
	v_add_u32_e32 v158, s64, v144
	s_barrier
	ds_read_b128 v[146:149], v158
	ds_read_b128 v[150:153], v158 offset:1024
	ds_read_b128 v[154:157], v158 offset:2048
	ds_read_b128 v[158:161], v158 offset:3072
	s_add_u32 s38, s38, 0x100000
	s_addc_u32 s39, s39, 0
	s_mov_b32 m0, s45
	v_lshl_add_u64 v[202:203], s[38:39], 0, v[128:129]
	ds_read_b128 v[162:165], v145 offset:32768
	ds_read_b128 v[166:169], v145 offset:33792
	ds_read_b128 v[174:177], v145 offset:34816
	ds_read_b128 v[178:181], v145 offset:35840
	ds_read_b128 v[186:189], v145 offset:36864
	ds_read_b128 v[190:193], v145 offset:37888
	ds_read_b128 v[194:197], v145 offset:38912
	ds_read_b128 v[198:201], v145 offset:39936
	global_load_lds_dwordx4 v[202:203], off
	v_lshl_add_u64 v[202:203], s[38:39], 0, v[130:131]
	s_mov_b32 m0, s46
	s_nop 0
	global_load_lds_dwordx4 v[202:203], off
	s_waitcnt lgkmcnt(8)
	s_barrier
	s_waitcnt lgkmcnt(0)
	s_waitcnt lgkmcnt(0)
	v_mfma_f32_16x16x32_bf16 v[124:127], v[146:149], v[162:165], v[124:127]
	v_mfma_f32_16x16x32_bf16 v[120:123], v[154:157], v[162:165], v[120:123]
	v_mfma_f32_16x16x32_bf16 v[108:111], v[146:149], v[174:177], v[108:111]
	v_mfma_f32_16x16x32_bf16 v[104:107], v[154:157], v[174:177], v[104:107]
	v_mfma_f32_16x16x32_bf16 v[92:95], v[146:149], v[186:189], v[92:95]
	v_mfma_f32_16x16x32_bf16 v[88:91], v[154:157], v[186:189], v[88:91]
	v_mfma_f32_16x16x32_bf16 v[76:79], v[146:149], v[194:197], v[76:79]
	v_mfma_f32_16x16x32_bf16 v[72:75], v[154:157], v[194:197], v[72:75]
	v_mfma_f32_16x16x32_bf16 v[124:127], v[150:153], v[166:169], v[124:127]
	v_mfma_f32_16x16x32_bf16 v[120:123], v[158:161], v[166:169], v[120:123]
	v_mfma_f32_16x16x32_bf16 v[108:111], v[150:153], v[178:181], v[108:111]
	v_mfma_f32_16x16x32_bf16 v[104:107], v[158:161], v[178:181], v[104:107]
	v_mfma_f32_16x16x32_bf16 v[92:95], v[150:153], v[190:193], v[92:95]
	v_mfma_f32_16x16x32_bf16 v[88:91], v[158:161], v[190:193], v[88:91]
	v_mfma_f32_16x16x32_bf16 v[76:79], v[150:153], v[198:201], v[76:79]
	v_mfma_f32_16x16x32_bf16 v[72:75], v[158:161], v[198:201], v[72:75]
	s_barrier
	s_add_i32 s38, 16, 0x1c000
	s_add_i32 s39, s64, s42
	v_add_u32_e32 v172, s38, v144
	v_lshl_add_u64 v[170:171], v[170:171], 0, s[12:13]
	s_mov_b32 m0, s39
	ds_read_b128 v[202:205], v172
	ds_read_b128 v[206:209], v172 offset:1024
	ds_read_b128 v[210:213], v172 offset:2048
	ds_read_b128 v[214:217], v172 offset:3072
	global_load_lds_dwordx4 v[170:171], off
	v_lshl_add_u64 v[170:171], v[182:183], 0, s[12:13]
	s_add_i32 m0, s39, 0x2000
	s_nop 0
	global_load_lds_dwordx4 v[170:171], off
	s_barrier
	s_waitcnt lgkmcnt(0)
	s_waitcnt lgkmcnt(0)
	v_mfma_f32_16x16x32_bf16 v[116:119], v[202:205], v[162:165], v[116:119]
	v_mfma_f32_16x16x32_bf16 v[112:115], v[210:213], v[162:165], v[112:115]
	v_mfma_f32_16x16x32_bf16 v[100:103], v[202:205], v[174:177], v[100:103]
	v_mfma_f32_16x16x32_bf16 v[96:99], v[210:213], v[174:177], v[96:99]
	v_mfma_f32_16x16x32_bf16 v[84:87], v[202:205], v[186:189], v[84:87]
	v_mfma_f32_16x16x32_bf16 v[80:83], v[210:213], v[186:189], v[80:83]
	v_mfma_f32_16x16x32_bf16 v[68:71], v[202:205], v[194:197], v[68:71]
	v_mfma_f32_16x16x32_bf16 v[64:67], v[210:213], v[194:197], v[64:67]
	v_mfma_f32_16x16x32_bf16 v[116:119], v[206:209], v[166:169], v[116:119]
	v_mfma_f32_16x16x32_bf16 v[112:115], v[214:217], v[166:169], v[112:115]
	v_mfma_f32_16x16x32_bf16 v[100:103], v[206:209], v[178:181], v[100:103]
	v_mfma_f32_16x16x32_bf16 v[96:99], v[214:217], v[178:181], v[96:99]
	v_mfma_f32_16x16x32_bf16 v[84:87], v[206:209], v[190:193], v[84:87]
	v_mfma_f32_16x16x32_bf16 v[80:83], v[214:217], v[190:193], v[80:83]
	v_mfma_f32_16x16x32_bf16 v[68:71], v[206:209], v[198:201], v[68:71]
	v_mfma_f32_16x16x32_bf16 v[64:67], v[214:217], v[198:201], v[64:67]
	s_mov_b32 m0, s47
	v_lshl_add_u64 v[170:171], v[218:219], 0, s[12:13]
	s_barrier
	ds_read_b128 v[162:165], v145 offset:49152
	ds_read_b128 v[166:169], v145 offset:50176
	ds_read_b128 v[174:177], v145 offset:51200
	ds_read_b128 v[178:181], v145 offset:52224
	ds_read_b128 v[186:189], v145 offset:53248
	ds_read_b128 v[190:193], v145 offset:54272
	ds_read_b128 v[194:197], v145 offset:55296
	ds_read_b128 v[198:201], v145 offset:56320
	global_load_lds_dwordx4 v[170:171], off
	v_lshl_add_u64 v[170:171], v[220:221], 0, s[12:13]
	s_mov_b32 m0, s48
	s_nop 0
	global_load_lds_dwordx4 v[170:171], off
	s_barrier
; #define PG8_STAGE(bufoff, gbase, voff) do { _Pragma("unroll") for (int _i = 0; _i < 2; ++_i) \
;         __builtin_amdgcn_global_load_lds((const unsigned*)((const char*)(gbase) + (voff)[_i]), (LAS unsigned*)(lds + (bufoff) + ldsw + _i * 8192), 16, 0, 0); } while (0)
; #define PG8_MMA(ai, bj, At, Bt) do { __builtin_amdgcn_s_setprio(1); _Pragma("unroll") for (int m = 0; m < 4; ++m) _Pragma("unroll") for (int n = 0; n < 2; ++n) _Pragma("unroll") for (int k = 0; k < 2; ++k) \
;         acc[ai][bj][m][n] = __builtin_amdgcn_mfma_f32_16x16x32_bf16(Bt[n][k], At[m][k], acc[ai][bj][m][n], 0, 0, 0); __builtin_amdgcn_s_setprio(0); } while (0)
; #define PG8_WAIT_V(n) asm volatile("s_waitcnt vmcnt(" #n ")" ::: "memory")
; #define PG8_WAIT_L(n) asm volatile("s_waitcnt lgkmcnt(" #n ")" ::: "memory")
; #define PG8_BAR __builtin_amdgcn_s_barrier()
; #define PG8_SCHED __builtin_amdgcn_sched_barrier(0)
; template <class Epi>
; __device__ __forceinline__ void gemm_phase(LAS unsigned char* lds, const Gemm g, const StaticOrder& S, const Epi& E, float* smem = nullptr) {
;     ...
;             PG8_BAR; PG8_WAIT_L(0); PG8_MMA(1, 0, At, B0); PG8_BAR; PG8_SCHED;
;             PG8_STAGE(PG8_SB(1, 1), b3 + hstep, voffA);
;             PG8_WAIT_V(6); PG8_BAR; PG8_MMA(1, 1, At, B1); PG8_BAR;
;         }
;         if constexpr (!Epi::AFTER_DRAIN) E(acc, cur, wr, wc, fr, fq);
;         if (!has_next) break;
; #pragma unroll
;         for (int a = 0; a < 2; ++a)
; #pragma unroll
;             for (int b = 0; b < 2; ++b)
; #pragma unroll
;                 for (int m = 0; m < 4; ++m)
; #pragma unroll
;                     for (int n = 0; n < 2; ++n) acc[a][b][m][n] = (f32x4){0.f, 0.f, 0.f, 0.f};
;         cur = nxt; cA = nA; cB = nB; ++ui;
	s_waitcnt lgkmcnt(0)
	s_waitcnt lgkmcnt(0)
	v_mfma_f32_16x16x32_bf16 v[60:63], v[146:149], v[162:165], v[60:63]
	v_mfma_f32_16x16x32_bf16 v[56:59], v[154:157], v[162:165], v[56:59]
	v_mfma_f32_16x16x32_bf16 v[44:47], v[146:149], v[174:177], v[44:47]
	v_mfma_f32_16x16x32_bf16 v[40:43], v[154:157], v[174:177], v[40:43]
	v_mfma_f32_16x16x32_bf16 v[28:31], v[146:149], v[186:189], v[28:31]
	v_mfma_f32_16x16x32_bf16 v[24:27], v[154:157], v[186:189], v[24:27]
	v_mfma_f32_16x16x32_bf16 v[12:15], v[146:149], v[194:197], v[12:15]
	v_mfma_f32_16x16x32_bf16 v[8:11], v[154:157], v[194:197], v[8:11]
	v_mfma_f32_16x16x32_bf16 v[60:63], v[150:153], v[166:169], v[60:63]
	v_mfma_f32_16x16x32_bf16 v[56:59], v[158:161], v[166:169], v[56:59]
	v_mfma_f32_16x16x32_bf16 v[44:47], v[150:153], v[178:181], v[44:47]
	v_mfma_f32_16x16x32_bf16 v[40:43], v[158:161], v[178:181], v[40:43]
	v_mfma_f32_16x16x32_bf16 v[28:31], v[150:153], v[190:193], v[28:31]
	v_mfma_f32_16x16x32_bf16 v[24:27], v[158:161], v[190:193], v[24:27]
	v_mfma_f32_16x16x32_bf16 v[12:15], v[150:153], v[198:201], v[12:15]
	v_mfma_f32_16x16x32_bf16 v[8:11], v[158:161], v[198:201], v[8:11]
	s_barrier
	s_add_u32 s36, s36, 0x100080
	s_addc_u32 s37, s37, 0
	s_add_i32 s38, s38, s42
	v_lshl_add_u64 v[146:147], s[36:37], 0, v[128:129]
	s_mov_b32 m0, s38
	s_nop 0
	global_load_lds_dwordx4 v[146:147], off
	v_lshl_add_u64 v[146:147], s[36:37], 0, v[130:131]
	s_add_i32 m0, s38, 0x2000
	s_nop 0
	global_load_lds_dwordx4 v[146:147], off
	s_waitcnt vmcnt(6)
	s_barrier
	v_mfma_f32_16x16x32_bf16 v[52:55], v[202:205], v[162:165], v[52:55]
	v_mfma_f32_16x16x32_bf16 v[48:51], v[210:213], v[162:165], v[48:51]
	v_mfma_f32_16x16x32_bf16 v[36:39], v[202:205], v[174:177], v[36:39]
	v_mfma_f32_16x16x32_bf16 v[32:35], v[210:213], v[174:177], v[32:35]
	v_mfma_f32_16x16x32_bf16 v[20:23], v[202:205], v[186:189], v[20:23]
	v_mfma_f32_16x16x32_bf16 v[16:19], v[210:213], v[186:189], v[16:19]
	v_mfma_f32_16x16x32_bf16 v[4:7], v[202:205], v[194:197], v[4:7]
	v_mfma_f32_16x16x32_bf16 v[0:3], v[210:213], v[194:197], v[0:3]
	v_mfma_f32_16x16x32_bf16 v[52:55], v[206:209], v[166:169], v[52:55]
	v_mfma_f32_16x16x32_bf16 v[48:51], v[214:217], v[166:169], v[48:51]
	v_mfma_f32_16x16x32_bf16 v[36:39], v[206:209], v[178:181], v[36:39]
	v_mfma_f32_16x16x32_bf16 v[32:35], v[214:217], v[178:181], v[32:35]
	v_mfma_f32_16x16x32_bf16 v[20:23], v[206:209], v[190:193], v[20:23]
	v_mfma_f32_16x16x32_bf16 v[16:19], v[214:217], v[190:193], v[16:19]
	v_mfma_f32_16x16x32_bf16 v[4:7], v[206:209], v[198:201], v[4:7]
	v_mfma_f32_16x16x32_bf16 v[0:3], v[214:217], v[198:201], v[0:3]
	s_add_i32 s63, s63, 2
	s_add_u32 s28, s28, 0x100
	s_addc_u32 s29, s29, 0
	s_cmp_gt_u32 s63, 61
	s_barrier
	s_cbranch_scc0 .LBB0_774
	s_add_u32 s28, s53, 0xffffff00
	s_addc_u32 s29, s60, -1
	s_andn2_b64 vcc, exec, s[4:5]
	s_cbranch_vccnz .LBB0_777
	v_mov_b32_e32 v0, 0
	s_mov_b32 s9, s14
	s_mov_b32 s8, s22
	s_mov_b64 s[10:11], s[26:27]
	s_mov_b32 s49, s52
	v_mov_b32_e32 v1, v0
	v_mov_b32_e32 v2, v0
	v_mov_b32_e32 v3, v0
	v_mov_b32_e32 v4, v0
	v_mov_b32_e32 v5, v0
	v_mov_b32_e32 v6, v0
	v_mov_b32_e32 v7, v0
	v_mov_b32_e32 v16, v0
	v_mov_b32_e32 v17, v0
	v_mov_b32_e32 v18, v0
	v_mov_b32_e32 v19, v0
	v_mov_b32_e32 v20, v0
	v_mov_b32_e32 v21, v0
	v_mov_b32_e32 v22, v0
	v_mov_b32_e32 v23, v0
	v_mov_b32_e32 v32, v0
	v_mov_b32_e32 v33, v0
	v_mov_b32_e32 v34, v0
	v_mov_b32_e32 v35, v0
	v_mov_b32_e32 v36, v0
	v_mov_b32_e32 v37, v0
	v_mov_b32_e32 v38, v0
	v_mov_b32_e32 v39, v0
	v_mov_b32_e32 v48, v0
	v_mov_b32_e32 v49, v0
	v_mov_b32_e32 v50, v0
	v_mov_b32_e32 v51, v0
	v_mov_b32_e32 v52, v0
	v_mov_b32_e32 v53, v0
	v_mov_b32_e32 v54, v0
	v_mov_b32_e32 v55, v0
	v_mov_b32_e32 v8, v0
	v_mov_b32_e32 v9, v0
	v_mov_b32_e32 v10, v0
	v_mov_b32_e32 v11, v0
	v_mov_b32_e32 v12, v0
	v_mov_b32_e32 v13, v0
	v_mov_b32_e32 v14, v0
	v_mov_b32_e32 v15, v0
	v_mov_b32_e32 v24, v0
	v_mov_b32_e32 v25, v0
	v_mov_b32_e32 v26, v0
	v_mov_b32_e32 v27, v0
	v_mov_b32_e32 v28, v0
	v_mov_b32_e32 v29, v0
	v_mov_b32_e32 v30, v0
	v_mov_b32_e32 v31, v0
	v_mov_b32_e32 v40, v0
	v_mov_b32_e32 v41, v0
	v_mov_b32_e32 v42, v0
	v_mov_b32_e32 v43, v0
	v_mov_b32_e32 v44, v0
	v_mov_b32_e32 v45, v0
	v_mov_b32_e32 v46, v0
	v_mov_b32_e32 v47, v0
	v_mov_b32_e32 v56, v0
	v_mov_b32_e32 v57, v0
	v_mov_b32_e32 v58, v0
	v_mov_b32_e32 v59, v0
	v_mov_b32_e32 v60, v0
	v_mov_b32_e32 v61, v0
	v_mov_b32_e32 v62, v0
	v_mov_b32_e32 v63, v0
	v_mov_b32_e32 v64, v0
	v_mov_b32_e32 v65, v0
	v_mov_b32_e32 v66, v0
	v_mov_b32_e32 v67, v0
	v_mov_b32_e32 v68, v0
	v_mov_b32_e32 v69, v0
	v_mov_b32_e32 v70, v0
	v_mov_b32_e32 v71, v0
	v_mov_b32_e32 v80, v0
	v_mov_b32_e32 v81, v0
	v_mov_b32_e32 v82, v0
	v_mov_b32_e32 v83, v0
	v_mov_b32_e32 v84, v0
	v_mov_b32_e32 v85, v0
	v_mov_b32_e32 v86, v0
	v_mov_b32_e32 v87, v0
	v_mov_b32_e32 v96, v0
	v_mov_b32_e32 v97, v0
	v_mov_b32_e32 v98, v0
	v_mov_b32_e32 v99, v0
	v_mov_b32_e32 v100, v0
	v_mov_b32_e32 v101, v0
	v_mov_b32_e32 v102, v0
	v_mov_b32_e32 v103, v0
	v_mov_b32_e32 v112, v0
	v_mov_b32_e32 v113, v0
	v_mov_b32_e32 v114, v0
	v_mov_b32_e32 v115, v0
	v_mov_b32_e32 v116, v0
	v_mov_b32_e32 v117, v0
	v_mov_b32_e32 v118, v0
	v_mov_b32_e32 v119, v0
	v_mov_b32_e32 v72, v0
	v_mov_b32_e32 v73, v0
	v_mov_b32_e32 v74, v0
	v_mov_b32_e32 v75, v0
	v_mov_b32_e32 v76, v0
	v_mov_b32_e32 v77, v0
	v_mov_b32_e32 v78, v0
	v_mov_b32_e32 v79, v0
	v_mov_b32_e32 v88, v0
	v_mov_b32_e32 v89, v0
	v_mov_b32_e32 v90, v0
	v_mov_b32_e32 v91, v0
	v_mov_b32_e32 v92, v0
	v_mov_b32_e32 v93, v0
	v_mov_b32_e32 v94, v0
	v_mov_b32_e32 v95, v0
	v_mov_b32_e32 v104, v0
	v_mov_b32_e32 v105, v0
	v_mov_b32_e32 v106, v0
	v_mov_b32_e32 v107, v0
	v_mov_b32_e32 v108, v0
	v_mov_b32_e32 v109, v0
	v_mov_b32_e32 v110, v0
	v_mov_b32_e32 v111, v0
	v_mov_b32_e32 v120, v0
	v_mov_b32_e32 v121, v0
	v_mov_b32_e32 v122, v0
	v_mov_b32_e32 v123, v0
	v_mov_b32_e32 v124, v0
	v_mov_b32_e32 v125, v0
	v_mov_b32_e32 v126, v0
	v_mov_b32_e32 v127, v0
	s_andn2_b64 vcc, exec, s[0:1]
	s_cbranch_vccnz .LBB0_778
	s_branch .LBB0_779
